# norm phase: hand-written fast path for latent bf16 rows, 8 rows per wave in flight, 16B accesses (on top of sc1 GEMM stores)
# speedup vs baseline: 1.0077x; 1.0077x over previous
.LBB0_166:
	s_cmp_lt_u32 s42, 4
	v_pk_mul_f32 v[176:177], v[82:83], v[156:157]
	s_cselect_b64 vcc, -1, 0
	v_pk_fma_f32 v[176:177], v[126:127], v[158:159], v[176:177] neg_lo:[0,0,1] neg_hi:[0,0,1]
	v_pk_mul_f32 v[158:159], v[82:83], v[158:159]
	v_cndmask_b32_e32 v142, 1.0, v232, vcc
	v_pk_mul_f32 v[164:165], v[84:85], v[160:161]
	v_pk_mul_f32 v[178:179], v[76:77], v[152:153]
	v_pk_mul_f32 v[180:181], v[74:75], v[148:149]
	v_pk_fma_f32 v[156:157], v[126:127], v[156:157], v[158:159]
	v_pk_fma_f32 v[164:165], v[128:129], v[162:163], v[164:165] neg_lo:[0,0,1] neg_hi:[0,0,1]
	v_pk_fma_f32 v[180:181], v[122:123], v[150:151], v[180:181] neg_lo:[0,0,1] neg_hi:[0,0,1]
	v_pk_fma_f32 v[178:179], v[124:125], v[154:155], v[178:179] neg_lo:[0,0,1] neg_hi:[0,0,1]
	v_pk_mul_f32 v[162:163], v[84:85], v[162:163]
	v_pk_mul_f32 v[156:157], v[142:143], v[156:157] op_sel_hi:[0,1]
	v_pk_mul_f32 v[154:155], v[76:77], v[154:155]
	v_pk_mul_f32 v[150:151], v[74:75], v[150:151]
	v_pk_fma_f32 v[158:159], v[128:129], v[160:161], v[162:163]
	v_pk_fma_f32 v[148:149], v[122:123], v[148:149], v[150:151]
	v_pk_fma_f32 v[150:151], v[124:125], v[152:153], v[154:155]
	v_cvt_pk_bf16_f32 v152, v156, v157
	v_mov_b64_e32 v[156:157], s[12:13]
	v_or_b32_e32 v0, s21, v171
	v_pk_mul_f32 v[164:165], v[142:143], v[164:165] op_sel_hi:[0,1]
	v_pk_mul_f32 v[176:177], v[142:143], v[176:177] op_sel_hi:[0,1]
	v_pk_mul_f32 v[178:179], v[142:143], v[178:179] op_sel_hi:[0,1]
	v_pk_mul_f32 v[180:181], v[142:143], v[180:181] op_sel_hi:[0,1]
	v_pk_mul_f32 v[158:159], v[142:143], v[158:159] op_sel_hi:[0,1]
	v_pk_mul_f32 v[160:161], v[142:143], v[150:151] op_sel_hi:[0,1]
	v_pk_mul_f32 v[154:155], v[142:143], v[148:149] op_sel_hi:[0,1]
	v_mad_i64_i32 v[156:157], s[42:43], v174, s91, v[156:157]
	v_cvt_pk_bf16_f32 v148, v176, v177
	v_cvt_pk_bf16_f32 v149, v164, v165
	v_cvt_pk_bf16_f32 v150, v180, v181
	v_cvt_pk_bf16_f32 v151, v178, v179
	v_cvt_pk_bf16_f32 v153, v158, v159
	v_cvt_pk_bf16_f32 v154, v154, v155
	v_cvt_pk_bf16_f32 v155, v160, v161
	v_lshl_add_u64 v[156:157], v[0:1], 1, v[156:157]
	v_cndmask_b32_e64 v143, 0, 1, s[26:27]
	s_lshr_b32 s22, s29, 6
	global_store_dwordx4 v[156:157], v[148:151], off sc1
	global_store_dwordx4 v[156:157], v[152:155], off offset:64 sc1
	v_or_b32_e32 v162, 16, v174
	v_cmp_ne_u32_e64 s[42:43], 1, v143
	s_andn2_b64 vcc, exec, s[26:27]
	v_mov_b32_e32 v147, 0
	v_mov_b32_e32 v150, 0
	v_mov_b32_e32 v151, 0
	v_mov_b32_e32 v154, 0
	v_mov_b32_e32 v155, 0
	v_mov_b32_e32 v158, 0
	v_mov_b32_e32 v159, 0
	v_mov_b32_e32 v145, 1.0
	v_mov_b32_e32 v152, 1.0
	v_mov_b32_e32 v153, 1.0
	v_mov_b32_e32 v156, 1.0
	v_mov_b32_e32 v157, 1.0
	v_mov_b32_e32 v160, 1.0
	v_mov_b32_e32 v161, 1.0
	s_cbranch_vccnz .LBB0_168
	v_mov_b32_e32 v143, s22
	v_cndmask_b32_e64 v143, v162, v143, s[38:39]
	v_and_b32_e32 v143, 63, v143
	v_cvt_f32_ubyte0_e32 v143, v143
	v_mul_f32_e32 v143, v168, v143
	v_mul_f32_e32 v146, 0.15915494, v143
	v_mul_f32_e32 v147, 0x3db74af8, v143
	v_mul_f32_e32 v148, 0x3d4e2601, v143
	v_mul_f32_e32 v149, 0x3ce7da22, v143
	v_mul_f32_e32 v150, 0x3c826136, v143
	v_mul_f32_e32 v151, 0x3c12a260, v143
	v_mul_f32_e32 v163, 0x3ba4eb34, v143
	v_mul_f32_e32 v143, 0x3b397b4e, v143
	v_cos_f32_e32 v156, v146
	v_cos_f32_e32 v157, v147
	v_cos_f32_e32 v160, v148
	v_cos_f32_e32 v161, v149
	v_cos_f32_e32 v144, v150
	v_cos_f32_e32 v145, v151
	v_cos_f32_e32 v152, v163
	v_cos_f32_e32 v153, v143
	v_sin_f32_e32 v154, v146
	v_sin_f32_e32 v155, v147
	v_sin_f32_e32 v158, v148
	v_sin_f32_e32 v159, v149
	v_sin_f32_e32 v146, v150
	v_sin_f32_e32 v147, v151
	v_sin_f32_e32 v150, v163
	v_sin_f32_e32 v151, v143
.LBB0_168:
	v_pk_mul_f32 v[164:165], v[70:71], v[154:155]
	v_mov_b32_e32 v143, v142
	v_pk_fma_f32 v[164:165], v[118:119], v[156:157], v[164:165] neg_lo:[0,0,1] neg_hi:[0,0,1]
	v_pk_mul_f32 v[156:157], v[70:71], v[156:157]
	v_pk_mul_f32 v[148:149], v[72:73], v[158:159]
	v_pk_mul_f32 v[178:179], v[64:65], v[150:151]
	v_pk_mul_f32 v[180:181], v[62:63], v[146:147]
	v_pk_fma_f32 v[154:155], v[118:119], v[154:155], v[156:157]
	v_pk_fma_f32 v[176:177], v[120:121], v[160:161], v[148:149] neg_lo:[0,0,1] neg_hi:[0,0,1]
	v_pk_fma_f32 v[180:181], v[114:115], v[144:145], v[180:181] neg_lo:[0,0,1] neg_hi:[0,0,1]
	v_pk_fma_f32 v[178:179], v[116:117], v[152:153], v[178:179] neg_lo:[0,0,1] neg_hi:[0,0,1]
	v_pk_mul_f32 v[160:161], v[72:73], v[160:161]
	v_pk_mul_f32 v[154:155], v[142:143], v[154:155]
	v_pk_mul_f32 v[152:153], v[64:65], v[152:153]
	v_pk_mul_f32 v[144:145], v[62:63], v[144:145]
	v_mov_b32_e32 v148, v142
	v_mov_b32_e32 v149, v142
	v_pk_fma_f32 v[156:157], v[120:121], v[158:159], v[160:161]
	v_pk_fma_f32 v[144:145], v[114:115], v[146:147], v[144:145]
	v_pk_fma_f32 v[146:147], v[116:117], v[150:151], v[152:153]
	v_cvt_pk_bf16_f32 v150, v154, v155
	v_mov_b64_e32 v[154:155], s[12:13]
	v_pk_mul_f32 v[176:177], v[148:149], v[176:177]
	v_pk_mul_f32 v[164:165], v[142:143], v[164:165]
	v_pk_mul_f32 v[178:179], v[148:149], v[178:179]
	v_pk_mul_f32 v[180:181], v[142:143], v[180:181]
	v_pk_mul_f32 v[156:157], v[148:149], v[156:157]
	v_pk_mul_f32 v[158:159], v[148:149], v[146:147]
	v_pk_mul_f32 v[152:153], v[142:143], v[144:145]
	v_mad_i64_i32 v[154:155], s[26:27], v162, s91, v[154:155]
	v_cvt_pk_bf16_f32 v144, v164, v165
	v_cvt_pk_bf16_f32 v145, v176, v177
	v_cvt_pk_bf16_f32 v146, v180, v181
	v_cvt_pk_bf16_f32 v147, v178, v179
	v_cvt_pk_bf16_f32 v151, v156, v157
	v_cvt_pk_bf16_f32 v152, v152, v153
	v_cvt_pk_bf16_f32 v153, v158, v159
	v_lshl_add_u64 v[154:155], v[0:1], 1, v[154:155]
	global_store_dwordx4 v[154:155], v[144:147], off sc1
	global_store_dwordx4 v[154:155], v[150:153], off offset:64 sc1
	s_and_b64 vcc, exec, s[42:43]
	v_or_b32_e32 v145, 32, v174
	v_mov_b32_e32 v144, 1.0
	v_mov_b32_e32 v146, 0
	v_mov_b32_e32 v150, 0
	v_mov_b32_e32 v151, 0
	v_mov_b32_e32 v154, 0
	v_mov_b32_e32 v155, 0
	v_mov_b32_e32 v158, 0
	v_mov_b32_e32 v159, 0
	v_mov_b32_e32 v162, 0
	v_mov_b32_e32 v163, 0
	v_mov_b32_e32 v152, 1.0
	v_mov_b32_e32 v153, 1.0
	v_mov_b32_e32 v156, 1.0
	v_mov_b32_e32 v157, 1.0
	v_mov_b32_e32 v160, 1.0
	v_mov_b32_e32 v161, 1.0
	v_mov_b32_e32 v164, 1.0
	v_mov_b32_e32 v165, 1.0
	s_cbranch_vccnz .LBB0_170
	v_mov_b32_e32 v147, s22
	v_cndmask_b32_e64 v147, v145, v147, s[38:39]
	v_and_b32_e32 v147, 63, v147
	v_cvt_f32_ubyte0_e32 v147, v147
	v_mul_f32_e32 v147, v168, v147
	v_mul_f32_e32 v150, 0.15915494, v147
	v_mul_f32_e32 v151, 0x3db74af8, v147
	v_mul_f32_e32 v154, 0x3d4e2601, v147
	v_mul_f32_e32 v155, 0x3ce7da22, v147
	v_mul_f32_e32 v175, 0x3c826136, v147
	v_mul_f32_e32 v176, 0x3c12a260, v147
	v_mul_f32_e32 v177, 0x3ba4eb34, v147
	v_mul_f32_e32 v147, 0x3b397b4e, v147
	v_cos_f32_e32 v160, v150
	v_cos_f32_e32 v161, v151
	v_cos_f32_e32 v164, v154
	v_cos_f32_e32 v165, v155
	v_cos_f32_e32 v152, v175
	v_cos_f32_e32 v153, v176
	v_cos_f32_e32 v156, v177
	v_cos_f32_e32 v157, v147
	v_sin_f32_e32 v158, v150
	v_sin_f32_e32 v159, v151
	v_sin_f32_e32 v162, v154
	v_sin_f32_e32 v163, v155
	v_sin_f32_e32 v150, v175
	v_sin_f32_e32 v151, v176
	v_sin_f32_e32 v154, v177
	v_sin_f32_e32 v155, v147
.LBB0_170:
	s_nop 0
	v_pk_mul_f32 v[180:181], v[48:49], v[154:155]
	v_pk_mul_f32 v[182:183], v[46:47], v[150:151]
	v_pk_fma_f32 v[180:181], v[108:109], v[156:157], v[180:181] neg_lo:[0,0,1] neg_hi:[0,0,1]
	v_pk_fma_f32 v[182:183], v[106:107], v[152:153], v[182:183] neg_lo:[0,0,1] neg_hi:[0,0,1]
	v_pk_mul_f32 v[156:157], v[48:49], v[156:157]
	v_pk_mul_f32 v[152:153], v[46:47], v[152:153]
	v_pk_mul_f32 v[176:177], v[56:57], v[162:163]
	v_pk_mul_f32 v[178:179], v[54:55], v[158:159]
	v_pk_fma_f32 v[150:151], v[106:107], v[150:151], v[152:153]
	v_pk_fma_f32 v[152:153], v[108:109], v[154:155], v[156:157]
	v_pk_fma_f32 v[178:179], v[110:111], v[160:161], v[178:179] neg_lo:[0,0,1] neg_hi:[0,0,1]
	v_pk_fma_f32 v[176:177], v[112:113], v[164:165], v[176:177] neg_lo:[0,0,1] neg_hi:[0,0,1]
	v_pk_mul_f32 v[164:165], v[56:57], v[164:165]
	v_pk_mul_f32 v[160:161], v[54:55], v[160:161]
	v_pk_mul_f32 v[156:157], v[148:149], v[152:153]
	v_pk_mul_f32 v[154:155], v[142:143], v[150:151]
	v_pk_fma_f32 v[158:159], v[110:111], v[158:159], v[160:161]
	v_pk_fma_f32 v[160:161], v[112:113], v[162:163], v[164:165]
	v_cvt_pk_bf16_f32 v154, v154, v155
	v_cvt_pk_bf16_f32 v155, v156, v157
	v_mov_b64_e32 v[156:157], s[12:13]
	v_pk_mul_f32 v[176:177], v[148:149], v[176:177]
	v_pk_mul_f32 v[178:179], v[142:143], v[178:179]
	v_pk_mul_f32 v[180:181], v[148:149], v[180:181]
	v_pk_mul_f32 v[182:183], v[142:143], v[182:183]
	v_pk_mul_f32 v[160:161], v[148:149], v[160:161]
	v_pk_mul_f32 v[158:159], v[142:143], v[158:159]
	v_mad_i64_i32 v[156:157], s[26:27], v145, s91, v[156:157]
	v_cvt_pk_bf16_f32 v148, v178, v179
	v_cvt_pk_bf16_f32 v149, v176, v177
	v_cvt_pk_bf16_f32 v150, v182, v183
	v_cvt_pk_bf16_f32 v151, v180, v181
	v_cvt_pk_bf16_f32 v152, v158, v159
	v_cvt_pk_bf16_f32 v153, v160, v161
	v_lshl_add_u64 v[156:157], v[0:1], 1, v[156:157]
	global_store_dwordx4 v[156:157], v[148:151], off sc1
	global_store_dwordx4 v[156:157], v[152:155], off offset:64 sc1
	v_or_b32_e32 v162, 48, v174
	s_and_b64 vcc, exec, s[42:43]
	v_mov_b32_e32 v147, 0
	v_mov_b32_e32 v150, 0
	v_mov_b32_e32 v151, 0
	v_mov_b32_e32 v154, 0
	v_mov_b32_e32 v155, 0
	v_mov_b32_e32 v158, 0
	v_mov_b32_e32 v159, 0
	v_mov_b32_e32 v145, 1.0
	v_mov_b32_e32 v152, 1.0
	v_mov_b32_e32 v153, 1.0
	v_mov_b32_e32 v156, 1.0
	v_mov_b32_e32 v157, 1.0
	v_mov_b32_e32 v160, 1.0
	v_mov_b32_e32 v161, 1.0
	s_cbranch_vccnz .LBB0_172
	v_mov_b32_e32 v144, s22
	v_cndmask_b32_e64 v144, v162, v144, s[38:39]
	v_and_b32_e32 v144, 63, v144
	v_cvt_f32_ubyte0_e32 v144, v144
	v_mul_f32_e32 v144, v168, v144
	v_mul_f32_e32 v146, 0.15915494, v144
	v_mul_f32_e32 v147, 0x3db74af8, v144
	v_mul_f32_e32 v148, 0x3d4e2601, v144
	v_mul_f32_e32 v149, 0x3ce7da22, v144
	v_mul_f32_e32 v150, 0x3c826136, v144
	v_mul_f32_e32 v151, 0x3c12a260, v144
	v_mul_f32_e32 v163, 0x3ba4eb34, v144
	v_mul_f32_e32 v164, 0x3b397b4e, v144
	v_cos_f32_e32 v156, v146
	v_cos_f32_e32 v157, v147
	v_cos_f32_e32 v160, v148
	v_cos_f32_e32 v161, v149
	v_cos_f32_e32 v144, v150
	v_cos_f32_e32 v145, v151
	v_cos_f32_e32 v152, v163
	v_cos_f32_e32 v153, v164
	v_sin_f32_e32 v154, v146
	v_sin_f32_e32 v155, v147
	v_sin_f32_e32 v158, v148
	v_sin_f32_e32 v159, v149
	v_sin_f32_e32 v146, v150
	v_sin_f32_e32 v147, v151
	v_sin_f32_e32 v150, v163
	v_sin_f32_e32 v151, v164
.LBB0_172:
	v_pk_mul_f32 v[164:165], v[38:39], v[154:155]
	v_pk_mul_f32 v[148:149], v[40:41], v[158:159]
	v_pk_fma_f32 v[164:165], v[102:103], v[156:157], v[164:165] neg_lo:[0,0,1] neg_hi:[0,0,1]
	v_pk_mul_f32 v[156:157], v[38:39], v[156:157]
	v_pk_mul_f32 v[178:179], v[36:37], v[150:151]
	v_pk_mul_f32 v[180:181], v[34:35], v[146:147]
	v_pk_fma_f32 v[154:155], v[102:103], v[154:155], v[156:157]
	v_pk_fma_f32 v[176:177], v[104:105], v[160:161], v[148:149] neg_lo:[0,0,1] neg_hi:[0,0,1]
	v_pk_fma_f32 v[180:181], v[98:99], v[144:145], v[180:181] neg_lo:[0,0,1] neg_hi:[0,0,1]
	v_pk_fma_f32 v[178:179], v[100:101], v[152:153], v[178:179] neg_lo:[0,0,1] neg_hi:[0,0,1]
	v_pk_mul_f32 v[160:161], v[40:41], v[160:161]
	v_pk_mul_f32 v[154:155], v[142:143], v[154:155]
	v_pk_mul_f32 v[152:153], v[36:37], v[152:153]
	v_pk_mul_f32 v[144:145], v[34:35], v[144:145]
	v_mov_b32_e32 v148, v142
	v_mov_b32_e32 v149, v142
	v_pk_fma_f32 v[156:157], v[104:105], v[158:159], v[160:161]
	v_pk_fma_f32 v[144:145], v[98:99], v[146:147], v[144:145]
	v_pk_fma_f32 v[146:147], v[100:101], v[150:151], v[152:153]
	v_cvt_pk_bf16_f32 v150, v154, v155
	v_mov_b64_e32 v[154:155], s[12:13]
	v_pk_mul_f32 v[176:177], v[148:149], v[176:177]
	v_pk_mul_f32 v[164:165], v[142:143], v[164:165]
	v_pk_mul_f32 v[178:179], v[148:149], v[178:179]
	v_pk_mul_f32 v[180:181], v[142:143], v[180:181]
	v_pk_mul_f32 v[156:157], v[148:149], v[156:157]
	v_pk_mul_f32 v[158:159], v[148:149], v[146:147]
	v_pk_mul_f32 v[152:153], v[142:143], v[144:145]
	v_mad_i64_i32 v[154:155], s[26:27], v162, s91, v[154:155]
	v_cvt_pk_bf16_f32 v144, v164, v165
	v_cvt_pk_bf16_f32 v145, v176, v177
	v_cvt_pk_bf16_f32 v146, v180, v181
	v_cvt_pk_bf16_f32 v147, v178, v179
	v_cvt_pk_bf16_f32 v151, v156, v157
	v_cvt_pk_bf16_f32 v152, v152, v153
	v_cvt_pk_bf16_f32 v153, v158, v159
	v_lshl_add_u64 v[154:155], v[0:1], 1, v[154:155]
	global_store_dwordx4 v[154:155], v[144:147], off sc1
	global_store_dwordx4 v[154:155], v[150:153], off offset:64 sc1
	s_and_b64 vcc, exec, s[42:43]
	v_add_u32_e32 v145, 0x80, v174
	v_mov_b32_e32 v144, 1.0
	v_mov_b32_e32 v146, 0
	v_mov_b32_e32 v150, 0
	v_mov_b32_e32 v151, 0
	v_mov_b32_e32 v154, 0
	v_mov_b32_e32 v155, 0
	v_mov_b32_e32 v158, 0
	v_mov_b32_e32 v159, 0
	v_mov_b32_e32 v162, 0
	v_mov_b32_e32 v163, 0
	v_mov_b32_e32 v152, 1.0
	v_mov_b32_e32 v153, 1.0
	v_mov_b32_e32 v156, 1.0
	v_mov_b32_e32 v157, 1.0
	v_mov_b32_e32 v160, 1.0
	v_mov_b32_e32 v161, 1.0
	v_mov_b32_e32 v164, 1.0
	v_mov_b32_e32 v165, 1.0
	s_cbranch_vccnz .LBB0_174
	v_bfe_u32 v147, v145, 6, 6
	v_cndmask_b32_e64 v147, v166, v147, s[38:39]
	v_cvt_f32_ubyte0_e32 v147, v147
	v_mul_f32_e32 v147, v168, v147
	v_mul_f32_e32 v150, 0.15915494, v147
	v_mul_f32_e32 v151, 0x3db74af8, v147
	v_mul_f32_e32 v154, 0x3d4e2601, v147
	v_mul_f32_e32 v155, 0x3ce7da22, v147
	v_mul_f32_e32 v175, 0x3c826136, v147
	v_mul_f32_e32 v176, 0x3c12a260, v147
	v_mul_f32_e32 v177, 0x3ba4eb34, v147
	v_mul_f32_e32 v147, 0x3b397b4e, v147
	v_cos_f32_e32 v160, v150
	v_cos_f32_e32 v161, v151
	v_cos_f32_e32 v164, v154
	v_cos_f32_e32 v165, v155
	v_cos_f32_e32 v152, v175
	v_cos_f32_e32 v153, v176
	v_cos_f32_e32 v156, v177
	v_cos_f32_e32 v157, v147
	v_sin_f32_e32 v158, v150
	v_sin_f32_e32 v159, v151
	v_sin_f32_e32 v162, v154
	v_sin_f32_e32 v163, v155
	v_sin_f32_e32 v150, v175
	v_sin_f32_e32 v151, v176
	v_sin_f32_e32 v154, v177
	v_sin_f32_e32 v155, v147
.LBB0_174:
	s_nop 0
	v_pk_mul_f32 v[180:181], v[28:29], v[154:155]
	v_pk_mul_f32 v[182:183], v[26:27], v[150:151]
	v_pk_fma_f32 v[180:181], v[92:93], v[156:157], v[180:181] neg_lo:[0,0,1] neg_hi:[0,0,1]
	v_pk_fma_f32 v[182:183], v[90:91], v[152:153], v[182:183] neg_lo:[0,0,1] neg_hi:[0,0,1]
	v_pk_mul_f32 v[156:157], v[28:29], v[156:157]
	v_pk_mul_f32 v[152:153], v[26:27], v[152:153]
	v_pk_mul_f32 v[176:177], v[32:33], v[162:163]
	v_pk_mul_f32 v[178:179], v[30:31], v[158:159]
	v_pk_fma_f32 v[150:151], v[90:91], v[150:151], v[152:153]
	v_pk_fma_f32 v[152:153], v[92:93], v[154:155], v[156:157]
	v_pk_fma_f32 v[178:179], v[94:95], v[160:161], v[178:179] neg_lo:[0,0,1] neg_hi:[0,0,1]
	v_pk_fma_f32 v[176:177], v[96:97], v[164:165], v[176:177] neg_lo:[0,0,1] neg_hi:[0,0,1]
	v_pk_mul_f32 v[164:165], v[32:33], v[164:165]
	v_pk_mul_f32 v[160:161], v[30:31], v[160:161]
	v_pk_mul_f32 v[156:157], v[148:149], v[152:153]
	v_pk_mul_f32 v[154:155], v[142:143], v[150:151]
	v_pk_fma_f32 v[158:159], v[94:95], v[158:159], v[160:161]
	v_pk_fma_f32 v[160:161], v[96:97], v[162:163], v[164:165]
	v_cvt_pk_bf16_f32 v154, v154, v155
	v_cvt_pk_bf16_f32 v155, v156, v157
	v_mov_b64_e32 v[156:157], s[12:13]
	v_pk_mul_f32 v[176:177], v[148:149], v[176:177]
	v_pk_mul_f32 v[178:179], v[142:143], v[178:179]
	v_pk_mul_f32 v[180:181], v[148:149], v[180:181]
	v_pk_mul_f32 v[182:183], v[142:143], v[182:183]
	v_pk_mul_f32 v[160:161], v[148:149], v[160:161]
	v_pk_mul_f32 v[158:159], v[142:143], v[158:159]
	v_mad_i64_i32 v[156:157], s[26:27], v145, s91, v[156:157]
	v_cvt_pk_bf16_f32 v148, v178, v179
	v_cvt_pk_bf16_f32 v149, v176, v177
	v_cvt_pk_bf16_f32 v150, v182, v183
	v_cvt_pk_bf16_f32 v151, v180, v181
	v_cvt_pk_bf16_f32 v152, v158, v159
	v_cvt_pk_bf16_f32 v153, v160, v161
	v_lshl_add_u64 v[156:157], v[0:1], 1, v[156:157]
	v_lshrrev_b32_e32 v175, 6, v145
	global_store_dwordx4 v[156:157], v[148:151], off sc1
	global_store_dwordx4 v[156:157], v[152:155], off offset:64 sc1
	v_add_u32_e32 v162, 0x90, v174
	s_and_b64 vcc, exec, s[42:43]
	v_mov_b32_e32 v147, 0
	v_mov_b32_e32 v150, 0
	v_mov_b32_e32 v151, 0
	v_mov_b32_e32 v154, 0
	v_mov_b32_e32 v155, 0
	v_mov_b32_e32 v158, 0
	v_mov_b32_e32 v159, 0
	v_mov_b32_e32 v145, 1.0
	v_mov_b32_e32 v152, 1.0
	v_mov_b32_e32 v153, 1.0
	v_mov_b32_e32 v156, 1.0
	v_mov_b32_e32 v157, 1.0
	v_mov_b32_e32 v160, 1.0
	v_mov_b32_e32 v161, 1.0
	s_cbranch_vccnz .LBB0_176
	v_cndmask_b32_e64 v144, v162, v175, s[38:39]
	v_and_b32_e32 v144, 63, v144
	v_cvt_f32_ubyte0_e32 v144, v144
	v_mul_f32_e32 v144, v168, v144
	v_mul_f32_e32 v146, 0.15915494, v144
	v_mul_f32_e32 v147, 0x3db74af8, v144
	v_mul_f32_e32 v148, 0x3d4e2601, v144
	v_mul_f32_e32 v149, 0x3ce7da22, v144
	v_mul_f32_e32 v150, 0x3c826136, v144
	v_mul_f32_e32 v151, 0x3c12a260, v144
	v_mul_f32_e32 v163, 0x3ba4eb34, v144
	v_mul_f32_e32 v164, 0x3b397b4e, v144
	v_cos_f32_e32 v156, v146
	v_cos_f32_e32 v157, v147
	v_cos_f32_e32 v160, v148
	v_cos_f32_e32 v161, v149
	v_cos_f32_e32 v144, v150
	v_cos_f32_e32 v145, v151
	v_cos_f32_e32 v152, v163
	v_cos_f32_e32 v153, v164
	v_sin_f32_e32 v154, v146
	v_sin_f32_e32 v155, v147
	v_sin_f32_e32 v158, v148
	v_sin_f32_e32 v159, v149
	v_sin_f32_e32 v146, v150
	v_sin_f32_e32 v147, v151
	v_sin_f32_e32 v150, v163
	v_sin_f32_e32 v151, v164
.LBB0_176:
	v_pk_mul_f32 v[164:165], v[22:23], v[154:155]
	v_pk_mul_f32 v[148:149], v[24:25], v[158:159]
	v_pk_fma_f32 v[164:165], v[86:87], v[156:157], v[164:165] neg_lo:[0,0,1] neg_hi:[0,0,1]
	v_pk_mul_f32 v[156:157], v[22:23], v[156:157]
	v_pk_mul_f32 v[178:179], v[20:21], v[150:151]
	v_pk_mul_f32 v[180:181], v[18:19], v[146:147]
	v_pk_fma_f32 v[154:155], v[86:87], v[154:155], v[156:157]
	v_pk_fma_f32 v[176:177], v[88:89], v[160:161], v[148:149] neg_lo:[0,0,1] neg_hi:[0,0,1]
	v_pk_fma_f32 v[180:181], v[78:79], v[144:145], v[180:181] neg_lo:[0,0,1] neg_hi:[0,0,1]
	v_pk_fma_f32 v[178:179], v[80:81], v[152:153], v[178:179] neg_lo:[0,0,1] neg_hi:[0,0,1]
	v_pk_mul_f32 v[160:161], v[24:25], v[160:161]
	v_pk_mul_f32 v[154:155], v[142:143], v[154:155]
	v_pk_mul_f32 v[152:153], v[20:21], v[152:153]
	v_pk_mul_f32 v[144:145], v[18:19], v[144:145]
	v_mov_b32_e32 v148, v142
	v_mov_b32_e32 v149, v142
	v_pk_fma_f32 v[156:157], v[88:89], v[158:159], v[160:161]
	v_pk_fma_f32 v[144:145], v[78:79], v[146:147], v[144:145]
	v_pk_fma_f32 v[146:147], v[80:81], v[150:151], v[152:153]
	v_cvt_pk_bf16_f32 v150, v154, v155
	v_mov_b64_e32 v[154:155], s[12:13]
	v_pk_mul_f32 v[176:177], v[148:149], v[176:177]
	v_pk_mul_f32 v[164:165], v[142:143], v[164:165]
	v_pk_mul_f32 v[178:179], v[148:149], v[178:179]
	v_pk_mul_f32 v[180:181], v[142:143], v[180:181]
	v_pk_mul_f32 v[156:157], v[148:149], v[156:157]
	v_pk_mul_f32 v[158:159], v[148:149], v[146:147]
	v_pk_mul_f32 v[152:153], v[142:143], v[144:145]
	v_mad_i64_i32 v[154:155], s[26:27], v162, s91, v[154:155]
	v_cvt_pk_bf16_f32 v144, v164, v165
	v_cvt_pk_bf16_f32 v145, v176, v177
	v_cvt_pk_bf16_f32 v146, v180, v181
	v_cvt_pk_bf16_f32 v147, v178, v179
	v_cvt_pk_bf16_f32 v151, v156, v157
	v_cvt_pk_bf16_f32 v152, v152, v153
	v_cvt_pk_bf16_f32 v153, v158, v159
	v_lshl_add_u64 v[154:155], v[0:1], 1, v[154:155]
	global_store_dwordx4 v[154:155], v[144:147], off sc1
	global_store_dwordx4 v[154:155], v[150:153], off offset:64 sc1
	s_and_b64 vcc, exec, s[42:43]
	v_add_u32_e32 v145, 0xa0, v174
	v_mov_b32_e32 v144, 1.0
	v_mov_b32_e32 v146, 0
	v_mov_b32_e32 v150, 0
	v_mov_b32_e32 v151, 0
	v_mov_b32_e32 v154, 0
	v_mov_b32_e32 v155, 0
	v_mov_b32_e32 v158, 0
	v_mov_b32_e32 v159, 0
	v_mov_b32_e32 v162, 0
	v_mov_b32_e32 v163, 0
	v_mov_b32_e32 v152, 1.0
	v_mov_b32_e32 v153, 1.0
	v_mov_b32_e32 v156, 1.0
	v_mov_b32_e32 v157, 1.0
	v_mov_b32_e32 v160, 1.0
	v_mov_b32_e32 v161, 1.0
	v_mov_b32_e32 v164, 1.0
	v_mov_b32_e32 v165, 1.0
	s_cbranch_vccnz .LBB0_178
	v_cndmask_b32_e64 v147, v145, v175, s[38:39]
	v_and_b32_e32 v147, 63, v147
	v_cvt_f32_ubyte0_e32 v147, v147
	v_mul_f32_e32 v147, v168, v147
	v_mul_f32_e32 v150, 0.15915494, v147
	v_mul_f32_e32 v151, 0x3db74af8, v147
	v_mul_f32_e32 v154, 0x3d4e2601, v147
	v_mul_f32_e32 v155, 0x3ce7da22, v147
	v_mul_f32_e32 v176, 0x3c826136, v147
	v_mul_f32_e32 v177, 0x3c12a260, v147
	v_mul_f32_e32 v178, 0x3ba4eb34, v147
	v_mul_f32_e32 v147, 0x3b397b4e, v147
	v_cos_f32_e32 v160, v150
	v_cos_f32_e32 v161, v151
	v_cos_f32_e32 v164, v154
	v_cos_f32_e32 v165, v155
	v_cos_f32_e32 v152, v176
	v_cos_f32_e32 v153, v177
	v_cos_f32_e32 v156, v178
	v_cos_f32_e32 v157, v147
	v_sin_f32_e32 v158, v150
	v_sin_f32_e32 v159, v151
	v_sin_f32_e32 v162, v154
	v_sin_f32_e32 v163, v155
	v_sin_f32_e32 v150, v176
	v_sin_f32_e32 v151, v177
	v_sin_f32_e32 v154, v178
	v_sin_f32_e32 v155, v147
.LBB0_178:
	s_nop 0
	v_pk_mul_f32 v[180:181], v[12:13], v[154:155]
	v_pk_mul_f32 v[182:183], v[10:11], v[150:151]
	v_pk_fma_f32 v[180:181], v[60:61], v[156:157], v[180:181] neg_lo:[0,0,1] neg_hi:[0,0,1]
	v_pk_fma_f32 v[182:183], v[58:59], v[152:153], v[182:183] neg_lo:[0,0,1] neg_hi:[0,0,1]
	v_pk_mul_f32 v[156:157], v[12:13], v[156:157]
	v_pk_mul_f32 v[152:153], v[10:11], v[152:153]
	v_pk_mul_f32 v[176:177], v[16:17], v[162:163]
	v_pk_mul_f32 v[178:179], v[14:15], v[158:159]
	v_pk_fma_f32 v[150:151], v[58:59], v[150:151], v[152:153]
	v_pk_fma_f32 v[152:153], v[60:61], v[154:155], v[156:157]
	v_pk_fma_f32 v[178:179], v[66:67], v[160:161], v[178:179] neg_lo:[0,0,1] neg_hi:[0,0,1]
	v_pk_fma_f32 v[176:177], v[68:69], v[164:165], v[176:177] neg_lo:[0,0,1] neg_hi:[0,0,1]
	v_pk_mul_f32 v[164:165], v[16:17], v[164:165]
	v_pk_mul_f32 v[160:161], v[14:15], v[160:161]
	v_pk_mul_f32 v[156:157], v[148:149], v[152:153]
	v_pk_mul_f32 v[154:155], v[142:143], v[150:151]
	v_pk_fma_f32 v[158:159], v[66:67], v[158:159], v[160:161]
	v_pk_fma_f32 v[160:161], v[68:69], v[162:163], v[164:165]
	v_cvt_pk_bf16_f32 v154, v154, v155
	v_cvt_pk_bf16_f32 v155, v156, v157
	v_mov_b64_e32 v[156:157], s[12:13]
	v_pk_mul_f32 v[176:177], v[148:149], v[176:177]
	v_pk_mul_f32 v[178:179], v[142:143], v[178:179]
	v_pk_mul_f32 v[180:181], v[148:149], v[180:181]
	v_pk_mul_f32 v[182:183], v[142:143], v[182:183]
	v_pk_mul_f32 v[160:161], v[148:149], v[160:161]
	v_pk_mul_f32 v[158:159], v[142:143], v[158:159]
	v_mad_i64_i32 v[156:157], s[26:27], v145, s91, v[156:157]
	v_cvt_pk_bf16_f32 v148, v178, v179
	v_cvt_pk_bf16_f32 v149, v176, v177
	v_cvt_pk_bf16_f32 v150, v182, v183
	v_cvt_pk_bf16_f32 v151, v180, v181
	v_cvt_pk_bf16_f32 v152, v158, v159
	v_cvt_pk_bf16_f32 v153, v160, v161
	v_lshl_add_u64 v[156:157], v[0:1], 1, v[156:157]
	global_store_dwordx4 v[156:157], v[148:151], off sc1
	global_store_dwordx4 v[156:157], v[152:155], off offset:64 sc1
	v_add_u32_e32 v160, 0xb0, v174
	s_and_b64 vcc, exec, s[42:43]
	v_mov_b32_e32 v147, 0
	v_mov_b32_e32 v148, 0
	v_mov_b32_e32 v149, 0
	v_mov_b32_e32 v152, 0
	v_mov_b32_e32 v153, 0
	v_mov_b32_e32 v156, 0
	v_mov_b32_e32 v157, 0
	v_mov_b32_e32 v145, 1.0
	v_mov_b32_e32 v150, 1.0
	v_mov_b32_e32 v151, 1.0
	v_mov_b32_e32 v154, 1.0
	v_mov_b32_e32 v155, 1.0
	v_mov_b32_e32 v158, 1.0
	v_mov_b32_e32 v159, 1.0
	s_cbranch_vccnz .LBB0_180
	v_cndmask_b32_e64 v144, v160, v175, s[38:39]
	v_and_b32_e32 v144, 63, v144
	v_cvt_f32_ubyte0_e32 v144, v144
	v_mul_f32_e32 v144, v168, v144
	v_mul_f32_e32 v146, 0.15915494, v144
	v_mul_f32_e32 v147, 0x3db74af8, v144
	v_mul_f32_e32 v148, 0x3d4e2601, v144
	v_mul_f32_e32 v149, 0x3ce7da22, v144
	v_mul_f32_e32 v161, 0x3c826136, v144
	v_mul_f32_e32 v162, 0x3c12a260, v144
	v_mul_f32_e32 v163, 0x3ba4eb34, v144
	v_mul_f32_e32 v164, 0x3b397b4e, v144
	v_cos_f32_e32 v154, v146
	v_cos_f32_e32 v155, v147
	v_cos_f32_e32 v158, v148
	v_cos_f32_e32 v159, v149
	v_cos_f32_e32 v144, v161
	v_cos_f32_e32 v145, v162
	v_cos_f32_e32 v150, v163
	v_cos_f32_e32 v151, v164
	v_sin_f32_e32 v152, v146
	v_sin_f32_e32 v153, v147
	v_sin_f32_e32 v156, v148
	v_sin_f32_e32 v157, v149
	v_sin_f32_e32 v146, v161
	v_sin_f32_e32 v147, v162
	v_sin_f32_e32 v148, v163
	v_sin_f32_e32 v149, v164
.LBB0_180:
	s_nop 0
	v_pk_mul_f32 v[178:179], v[4:5], v[148:149]
	v_pk_mul_f32 v[180:181], v[2:3], v[146:147]
	v_pk_fma_f32 v[178:179], v[44:45], v[150:151], v[178:179] neg_lo:[0,0,1] neg_hi:[0,0,1]
	v_pk_fma_f32 v[180:181], v[42:43], v[144:145], v[180:181] neg_lo:[0,0,1] neg_hi:[0,0,1]
	v_pk_mul_f32 v[150:151], v[4:5], v[150:151]
	v_pk_mul_f32 v[144:145], v[2:3], v[144:145]
	v_mov_b32_e32 v176, v142
	v_mov_b32_e32 v177, v142
	v_pk_fma_f32 v[144:145], v[42:43], v[146:147], v[144:145]
	v_pk_fma_f32 v[146:147], v[44:45], v[148:149], v[150:151]
	v_pk_mul_f32 v[162:163], v[8:9], v[156:157]
	v_pk_mul_f32 v[164:165], v[6:7], v[152:153]
	v_pk_mul_f32 v[150:151], v[176:177], v[146:147]
	v_pk_mul_f32 v[148:149], v[142:143], v[144:145]
	v_pk_fma_f32 v[164:165], v[50:51], v[154:155], v[164:165] neg_lo:[0,0,1] neg_hi:[0,0,1]
	v_pk_fma_f32 v[162:163], v[52:53], v[158:159], v[162:163] neg_lo:[0,0,1] neg_hi:[0,0,1]
	v_pk_mul_f32 v[158:159], v[8:9], v[158:159]
	v_pk_mul_f32 v[154:155], v[6:7], v[154:155]
	v_cvt_pk_bf16_f32 v148, v148, v149
	v_cvt_pk_bf16_f32 v149, v150, v151
	v_mov_b64_e32 v[150:151], s[12:13]
	v_pk_mul_f32 v[162:163], v[176:177], v[162:163]
	v_pk_mul_f32 v[164:165], v[142:143], v[164:165]
	v_pk_mul_f32 v[178:179], v[176:177], v[178:179]
	v_pk_mul_f32 v[180:181], v[142:143], v[180:181]
	v_pk_fma_f32 v[152:153], v[50:51], v[152:153], v[154:155]
	v_pk_fma_f32 v[154:155], v[52:53], v[156:157], v[158:159]
	v_mad_i64_i32 v[150:151], s[26:27], v160, s91, v[150:151]
	v_pk_mul_f32 v[154:155], v[176:177], v[154:155]
	v_pk_mul_f32 v[152:153], v[142:143], v[152:153]
	v_cvt_pk_bf16_f32 v142, v164, v165
	v_cvt_pk_bf16_f32 v143, v162, v163
	v_cvt_pk_bf16_f32 v144, v180, v181
	v_cvt_pk_bf16_f32 v145, v178, v179
	v_lshl_add_u64 v[150:151], v[0:1], 1, v[150:151]
	v_cvt_pk_bf16_f32 v146, v152, v153
	v_cvt_pk_bf16_f32 v147, v154, v155
	global_store_dwordx4 v[150:151], v[142:145], off sc1
	global_store_dwordx4 v[150:151], v[146:149], off offset:64 sc1

.LBB0_182:
	s_and_b64 vcc, exec, s[26:27]
	s_cbranch_vccz .LBB0_181
	v_or_b32_e32 v0, s21, v172
	v_cndmask_b32_e64 v142, v169, v0, s[40:41]
	v_ashrrev_i32_e32 v143, 31, v142
	v_cvt_pk_bf16_f32 v126, v126, v127
	v_cvt_pk_bf16_f32 v127, v128, v129
	v_cvt_pk_bf16_f32 v128, v122, v123
	v_mov_b64_e32 v[122:123], s[12:13]
	v_cvt_pk_bf16_f32 v66, v66, v67
	v_cvt_pk_bf16_f32 v67, v68, v69
	v_cvt_pk_bf16_f32 v68, v58, v59
	v_add_u32_e32 v58, 0xa0, v174
	v_lshlrev_b64 v[142:143], 1, v[142:143]
	v_mad_i64_i32 v[58:59], s[26:27], v58, s91, v[122:123]
	v_cvt_pk_bf16_f32 v69, v60, v61
	v_lshl_add_u64 v[60:61], v[58:59], 0, v[142:143]
	v_cvt_pk_bf16_f32 v50, v50, v51
	v_cvt_pk_bf16_f32 v51, v52, v53
	v_cvt_pk_bf16_f32 v52, v42, v43
	v_add_u32_e32 v42, 0xb0, v174
	v_cvt_pk_bf16_f32 v102, v102, v103
	v_cvt_pk_bf16_f32 v103, v104, v105
	v_cvt_pk_bf16_f32 v104, v98, v99
	v_or_b32_e32 v98, 48, v174
	global_store_dwordx4 v[60:61], v[66:69], off sc1
	v_mad_i64_i32 v[60:61], s[26:27], v42, s91, v[122:123]
	v_mad_i64_i32 v[98:99], s[26:27], v98, s91, v[122:123]
	v_cvt_pk_bf16_f32 v53, v44, v45
	v_lshl_add_u64 v[42:43], v[60:61], 0, v[142:143]
	v_or_b32_e32 v0, 0x80, v0
	v_cvt_pk_bf16_f32 v105, v100, v101
	v_lshl_add_u64 v[100:101], v[98:99], 0, v[142:143]
	global_store_dwordx4 v[42:43], v[50:53], off sc1
	v_cvt_pk_bf16_f32 v118, v118, v119
	v_cvt_pk_bf16_f32 v119, v120, v121
	v_cndmask_b32_e64 v50, v170, v0, s[40:41]
	v_cvt_pk_bf16_f32 v120, v114, v115
	v_or_b32_e32 v114, 16, v174
	v_cvt_pk_bf16_f32 v110, v110, v111
	v_cvt_pk_bf16_f32 v111, v112, v113
	v_cvt_pk_bf16_f32 v112, v106, v107
	v_or_b32_e32 v106, 32, v174
	global_store_dwordx4 v[100:101], v[102:105], off sc1
	v_add_u32_e32 v100, 0x80, v174
	v_cvt_pk_bf16_f32 v86, v86, v87
	v_cvt_pk_bf16_f32 v87, v88, v89
	v_cvt_pk_bf16_f32 v88, v78, v79
	v_add_u32_e32 v78, 0x90, v174
	v_ashrrev_i32_e32 v51, 31, v50
	v_cvt_pk_bf16_f32 v129, v124, v125
	v_mad_i64_i32 v[124:125], s[26:27], v174, s91, v[122:123]
	v_mad_i64_i32 v[114:115], s[26:27], v114, s91, v[122:123]
	v_mad_i64_i32 v[106:107], s[26:27], v106, s91, v[122:123]
	v_cvt_pk_bf16_f32 v94, v94, v95
	v_cvt_pk_bf16_f32 v95, v96, v97
	v_cvt_pk_bf16_f32 v96, v90, v91
	v_mad_i64_i32 v[90:91], s[26:27], v100, s91, v[122:123]
	v_mad_i64_i32 v[78:79], s[26:27], v78, s91, v[122:123]
	v_lshlrev_b64 v[50:51], 1, v[50:51]
	v_lshl_add_u64 v[144:145], v[124:125], 0, v[142:143]
	v_cvt_pk_bf16_f32 v121, v116, v117
	v_lshl_add_u64 v[116:117], v[114:115], 0, v[142:143]
	v_cvt_pk_bf16_f32 v113, v108, v109
	v_lshl_add_u64 v[108:109], v[106:107], 0, v[142:143]
	v_cvt_pk_bf16_f32 v97, v92, v93
	v_lshl_add_u64 v[92:93], v[90:91], 0, v[142:143]
	v_cvt_pk_bf16_f32 v89, v80, v81
	v_lshl_add_u64 v[80:81], v[78:79], 0, v[142:143]
	v_cvt_pk_bf16_f32 v42, v82, v83
	v_cvt_pk_bf16_f32 v43, v84, v85
	v_cvt_pk_bf16_f32 v44, v74, v75
	v_cvt_pk_bf16_f32 v45, v76, v77
	v_lshl_add_u64 v[52:53], v[124:125], 0, v[50:51]
	global_store_dwordx4 v[144:145], v[126:129], off sc1
	global_store_dwordx4 v[116:117], v[118:121], off sc1
	global_store_dwordx4 v[108:109], v[110:113], off sc1
	global_store_dwordx4 v[92:93], v[94:97], off sc1
	global_store_dwordx4 v[80:81], v[86:89], off sc1
	global_store_dwordx4 v[52:53], v[42:45], off sc1
	v_lshl_add_u64 v[52:53], v[114:115], 0, v[50:51]
	v_cvt_pk_bf16_f32 v38, v38, v39
	v_cvt_pk_bf16_f32 v42, v70, v71
	v_cvt_pk_bf16_f32 v43, v72, v73
	v_cvt_pk_bf16_f32 v44, v62, v63
	v_cvt_pk_bf16_f32 v45, v64, v65
	global_store_dwordx4 v[52:53], v[42:45], off sc1
	v_cvt_pk_bf16_f32 v39, v40, v41
	v_cvt_pk_bf16_f32 v40, v34, v35
	v_cvt_pk_bf16_f32 v42, v54, v55
	v_cvt_pk_bf16_f32 v43, v56, v57
	v_cvt_pk_bf16_f32 v44, v46, v47
	v_cvt_pk_bf16_f32 v45, v48, v49
	v_lshl_add_u64 v[46:47], v[106:107], 0, v[50:51]
	v_cvt_pk_bf16_f32 v41, v36, v37
	v_lshl_add_u64 v[34:35], v[98:99], 0, v[50:51]
	v_cvt_pk_bf16_f32 v30, v30, v31
	v_cvt_pk_bf16_f32 v31, v32, v33
	v_cvt_pk_bf16_f32 v32, v26, v27
	v_cvt_pk_bf16_f32 v33, v28, v29
	v_lshl_add_u64 v[26:27], v[90:91], 0, v[50:51]
	v_cvt_pk_bf16_f32 v22, v22, v23
	v_cvt_pk_bf16_f32 v23, v24, v25
	v_cvt_pk_bf16_f32 v24, v18, v19
	v_cvt_pk_bf16_f32 v25, v20, v21
	v_lshl_add_u64 v[18:19], v[78:79], 0, v[50:51]
	v_cvt_pk_bf16_f32 v14, v14, v15
	v_cvt_pk_bf16_f32 v15, v16, v17
	v_cvt_pk_bf16_f32 v16, v10, v11
	v_cvt_pk_bf16_f32 v17, v12, v13
	v_lshl_add_u64 v[10:11], v[58:59], 0, v[50:51]
	v_cvt_pk_bf16_f32 v6, v6, v7
	v_cvt_pk_bf16_f32 v7, v8, v9
	v_cvt_pk_bf16_f32 v8, v2, v3
	v_cvt_pk_bf16_f32 v9, v4, v5
	v_lshl_add_u64 v[2:3], v[60:61], 0, v[50:51]
	global_store_dwordx4 v[46:47], v[42:45], off sc1
	global_store_dwordx4 v[34:35], v[38:41], off sc1
	global_store_dwordx4 v[26:27], v[30:33], off sc1
	global_store_dwordx4 v[18:19], v[22:25], off sc1
	global_store_dwordx4 v[10:11], v[14:17], off sc1
	global_store_dwordx4 v[2:3], v[6:9], off sc1
	s_andn2_b64 vcc, exec, s[18:19]
	s_mov_b64 s[18:19], -1
	s_cbranch_vccnz .LBB0_149

.LBB0_220:
	s_min_i32 s13, s43, 64
	s_ashr_i32 s13, s13, 4
	s_mul_hi_i32 s23, s13, 0x9000
	s_mul_i32 s13, s13, 0x9000
	s_add_u32 s28, s53, s13
	v_lshl_or_b32 v154, s58, 8, v183
	s_addc_u32 s29, s94, s23
	v_ashrrev_i32_e32 v155, 31, v154
	v_lshl_add_u64 v[162:163], v[154:155], 2, s[28:29]
	global_load_dwordx4 v[130:133], v[162:163], off offset:16
	global_load_dwordx4 v[134:137], v[162:163], off
	v_mov_b32_e32 v145, v144
	s_cmp_gt_i32 s43, 63
	s_cselect_b64 s[30:31], -1, 0
	s_lshl_b32 s13, s43, 8
	s_cmp_lg_u32 s42, 0
	s_mov_b64 s[40:41], -1
	s_cselect_b64 s[28:29], -1, 0
	s_cmp_eq_u32 s42, 0
	s_waitcnt vmcnt(0)
	v_pk_mul_f32 v[156:157], v[144:145], v[132:133]
	v_pk_mul_f32 v[158:159], v[144:145], v[136:137]
	v_pk_mul_f32 v[160:161], v[146:147], v[134:135]
	v_pk_mul_f32 v[152:153], v[146:147], v[130:131]
	global_load_dwordx4 v[130:133], v[162:163], off offset:528
	global_load_dwordx4 v[134:137], v[162:163], off offset:512
	v_add_u32_e32 v162, s13, v174
	v_ashrrev_i32_e32 v163, 31, v162
	v_lshlrev_b64 v[162:163], 10, v[162:163]
	v_lshl_add_u64 v[162:163], v[162:163], 0, v[154:155]
	v_pk_mul_f32 v[168:169], v[128:129], v[158:159]
	v_pk_mul_f32 v[170:171], v[126:127], v[160:161]
	v_pk_mul_f32 v[164:165], v[124:125], v[156:157]
	v_pk_mul_f32 v[166:167], v[122:123], v[152:153]
	s_cbranch_scc1 .LBB0_222
	s_ashr_i32 s40, s12, 2
	s_ashr_i32 s41, s40, 31
	s_lshl_b64 s[40:41], s[40:41], 21
	s_add_u32 s40, s10, s40
	s_addc_u32 s41, s11, s41
	v_lshl_add_u64 v[126:127], v[162:163], 1, s[40:41]
	v_add_co_u32_e32 v126, vcc, 0xfe000000, v126
	v_cvt_pk_bf16_f32 v122, v170, v171
	v_cvt_pk_bf16_f32 v123, v168, v169
	v_cvt_pk_bf16_f32 v124, v166, v167
	v_cvt_pk_bf16_f32 v125, v164, v165
	v_addc_co_u32_e32 v127, vcc, -1, v127, vcc
	s_mov_b64 s[40:41], 0
	global_store_dwordx4 v[126:127], v[122:125], off sc1

.LBB0_227:
	s_waitcnt vmcnt(0)
	v_pk_add_f32 v[124:125], v[168:169], v[124:125]
	v_pk_add_f32 v[122:123], v[170:171], v[122:123]
	v_pk_add_f32 v[128:129], v[164:165], v[128:129]
	v_pk_add_f32 v[126:127], v[166:167], v[126:127]
	v_cvt_pk_bf16_f32 v122, v122, v123
	v_cvt_pk_bf16_f32 v123, v124, v125
	v_cvt_pk_bf16_f32 v124, v126, v127
	v_cvt_pk_bf16_f32 v125, v128, v129
	global_store_dwordx4 v[172:173], v[122:125], off sc1
.LBB0_228:
	v_mov_b32_e32 v145, v144
	s_waitcnt vmcnt(1)
	v_pk_mul_f32 v[124:125], v[144:145], v[132:133]
	s_waitcnt vmcnt(0)
	v_pk_mul_f32 v[126:127], v[144:145], v[136:137]
	v_pk_mul_f32 v[128:129], v[146:147], v[134:135]
	v_pk_mul_f32 v[122:123], v[146:147], v[130:131]
	v_pk_mul_f32 v[130:131], v[116:117], v[124:125]
	v_cndmask_b32_e64 v116, 0, 1, s[28:29]
	v_pk_mul_f32 v[132:133], v[120:121], v[126:127]
	v_pk_mul_f32 v[134:135], v[118:119], v[128:129]
	v_cmp_ne_u32_e64 s[42:43], 1, v116
	s_andn2_b64 vcc, exec, s[28:29]
	v_pk_mul_f32 v[136:137], v[114:115], v[122:123]
	s_cbranch_vccnz .LBB0_230
	s_ashr_i32 s28, s12, 2
	s_ashr_i32 s29, s28, 31
	s_lshl_b64 s[28:29], s[28:29], 21
	s_add_u32 s28, s10, s28
	s_addc_u32 s29, s11, s29
	v_lshl_add_u64 v[118:119], v[162:163], 1, s[28:29]
	v_add_co_u32_e32 v118, vcc, 0xfe001000, v118
	v_cvt_pk_bf16_f32 v114, v134, v135
	v_cvt_pk_bf16_f32 v115, v132, v133
	v_cvt_pk_bf16_f32 v116, v136, v137
	v_cvt_pk_bf16_f32 v117, v130, v131
	v_addc_co_u32_e32 v119, vcc, -1, v119, vcc
	global_store_dwordx4 v[118:119], v[114:117], off offset:-3840 sc1
	s_nop 1
	v_cndmask_b32_e64 v114, 0, 1, s[30:31]
	v_cmp_ne_u32_e64 s[40:41], 1, v114
	s_cbranch_execz .LBB0_231
	s_branch .LBB0_236

.LBB0_235:
	s_waitcnt vmcnt(0)
	v_pk_add_f32 v[116:117], v[132:133], v[116:117]
	v_pk_add_f32 v[114:115], v[134:135], v[114:115]
	v_pk_add_f32 v[120:121], v[130:131], v[120:121]
	v_pk_add_f32 v[118:119], v[136:137], v[118:119]
	v_cvt_pk_bf16_f32 v114, v114, v115
	v_cvt_pk_bf16_f32 v115, v116, v117
	v_cvt_pk_bf16_f32 v116, v118, v119
	v_cvt_pk_bf16_f32 v117, v120, v121
	global_store_dwordx4 v[164:165], v[114:117], off sc1
.LBB0_236:
	s_nop 1
	v_add_u32_e32 v114, s13, v176
	v_ashrrev_i32_e32 v115, 31, v114
	v_lshlrev_b64 v[114:115], 10, v[114:115]
	v_lshl_add_u64 v[114:115], v[114:115], 0, v[154:155]
	v_pk_mul_f32 v[116:117], v[112:113], v[158:159]
	v_pk_mul_f32 v[118:119], v[110:111], v[160:161]
	v_pk_mul_f32 v[120:121], v[108:109], v[156:157]
	s_and_b64 vcc, exec, s[42:43]
	v_pk_mul_f32 v[130:131], v[106:107], v[152:153]
	s_cbranch_vccnz .LBB0_238
	s_ashr_i32 s28, s12, 2
	s_ashr_i32 s29, s28, 31
	s_lshl_b64 s[28:29], s[28:29], 21
	s_add_u32 s28, s10, s28
	s_addc_u32 s29, s11, s29
	v_lshl_add_u64 v[110:111], v[114:115], 1, s[28:29]
	v_add_co_u32_e32 v110, vcc, 0xfe000000, v110
	v_cvt_pk_bf16_f32 v106, v118, v119
	v_cvt_pk_bf16_f32 v107, v116, v117
	v_cvt_pk_bf16_f32 v108, v130, v131
	v_cvt_pk_bf16_f32 v109, v120, v121
	v_addc_co_u32_e32 v111, vcc, -1, v111, vcc
	global_store_dwordx4 v[110:111], v[106:109], off sc1
	s_cbranch_execz .LBB0_239
	s_branch .LBB0_244

.LBB0_243:
	s_waitcnt vmcnt(0)
	v_pk_add_f32 v[108:109], v[116:117], v[108:109]
	v_pk_add_f32 v[106:107], v[118:119], v[106:107]
	v_pk_add_f32 v[112:113], v[120:121], v[112:113]
	v_pk_add_f32 v[110:111], v[130:131], v[110:111]
	v_cvt_pk_bf16_f32 v106, v106, v107
	v_cvt_pk_bf16_f32 v107, v108, v109
	v_cvt_pk_bf16_f32 v108, v110, v111
	v_cvt_pk_bf16_f32 v109, v112, v113
	global_store_dwordx4 v[132:133], v[106:109], off sc1
.LBB0_244:
	s_nop 1
	v_pk_mul_f32 v[106:107], v[104:105], v[126:127]
	v_pk_mul_f32 v[108:109], v[102:103], v[128:129]
	v_pk_mul_f32 v[110:111], v[100:101], v[124:125]
	s_and_b64 vcc, exec, s[42:43]
	v_pk_mul_f32 v[112:113], v[98:99], v[122:123]
	s_cbranch_vccnz .LBB0_246
	s_ashr_i32 s28, s12, 2
	s_ashr_i32 s29, s28, 31
	s_lshl_b64 s[28:29], s[28:29], 21
	s_add_u32 s28, s10, s28
	s_addc_u32 s29, s11, s29
	v_lshl_add_u64 v[102:103], v[114:115], 1, s[28:29]
	v_add_co_u32_e32 v102, vcc, 0xfe001000, v102
	v_cvt_pk_bf16_f32 v98, v108, v109
	v_cvt_pk_bf16_f32 v99, v106, v107
	v_cvt_pk_bf16_f32 v100, v112, v113
	v_cvt_pk_bf16_f32 v101, v110, v111
	v_addc_co_u32_e32 v103, vcc, -1, v103, vcc
	global_store_dwordx4 v[102:103], v[98:101], off offset:-3840 sc1
	s_cbranch_execz .LBB0_247
	s_branch .LBB0_252

.LBB0_251:
	s_waitcnt vmcnt(0)
	v_pk_add_f32 v[100:101], v[106:107], v[100:101]
	v_pk_add_f32 v[98:99], v[108:109], v[98:99]
	v_pk_add_f32 v[104:105], v[110:111], v[104:105]
	v_pk_add_f32 v[102:103], v[112:113], v[102:103]
	v_cvt_pk_bf16_f32 v98, v98, v99
	v_cvt_pk_bf16_f32 v99, v100, v101
	v_cvt_pk_bf16_f32 v100, v102, v103
	v_cvt_pk_bf16_f32 v101, v104, v105
	global_store_dwordx4 v[116:117], v[98:101], off sc1
.LBB0_252:
	s_nop 1
	v_add_u32_e32 v98, s13, v177
	v_ashrrev_i32_e32 v99, 31, v98
	v_lshlrev_b64 v[98:99], 10, v[98:99]
	v_lshl_add_u64 v[98:99], v[98:99], 0, v[154:155]
	v_pk_mul_f32 v[100:101], v[96:97], v[158:159]
	v_pk_mul_f32 v[102:103], v[94:95], v[160:161]
	v_pk_mul_f32 v[104:105], v[92:93], v[156:157]
	s_and_b64 vcc, exec, s[42:43]
	v_pk_mul_f32 v[106:107], v[90:91], v[152:153]
	s_cbranch_vccnz .LBB0_254
	s_ashr_i32 s28, s12, 2
	s_ashr_i32 s29, s28, 31
	s_lshl_b64 s[28:29], s[28:29], 21
	s_add_u32 s28, s10, s28
	s_addc_u32 s29, s11, s29
	v_lshl_add_u64 v[94:95], v[98:99], 1, s[28:29]
	v_add_co_u32_e32 v94, vcc, 0xfe000000, v94
	v_cvt_pk_bf16_f32 v90, v102, v103
	v_cvt_pk_bf16_f32 v91, v100, v101
	v_cvt_pk_bf16_f32 v92, v106, v107
	v_cvt_pk_bf16_f32 v93, v104, v105
	v_addc_co_u32_e32 v95, vcc, -1, v95, vcc
	global_store_dwordx4 v[94:95], v[90:93], off sc1
	s_cbranch_execz .LBB0_255
	s_branch .LBB0_260

.LBB0_259:
	s_waitcnt vmcnt(0)
	v_pk_add_f32 v[92:93], v[100:101], v[92:93]
	v_pk_add_f32 v[90:91], v[102:103], v[90:91]
	v_pk_add_f32 v[96:97], v[104:105], v[96:97]
	v_pk_add_f32 v[94:95], v[106:107], v[94:95]
	v_cvt_pk_bf16_f32 v90, v90, v91
	v_cvt_pk_bf16_f32 v91, v92, v93
	v_cvt_pk_bf16_f32 v92, v94, v95
	v_cvt_pk_bf16_f32 v93, v96, v97
	global_store_dwordx4 v[108:109], v[90:93], off sc1
.LBB0_260:
	s_nop 1
	v_pk_mul_f32 v[90:91], v[88:89], v[126:127]
	v_pk_mul_f32 v[92:93], v[86:87], v[128:129]
	v_pk_mul_f32 v[94:95], v[84:85], v[124:125]
	s_and_b64 vcc, exec, s[42:43]
	v_pk_mul_f32 v[96:97], v[82:83], v[122:123]
	s_cbranch_vccnz .LBB0_262
	s_ashr_i32 s28, s12, 2
	s_ashr_i32 s29, s28, 31
	s_lshl_b64 s[28:29], s[28:29], 21
	s_add_u32 s28, s10, s28
	s_addc_u32 s29, s11, s29
	v_lshl_add_u64 v[86:87], v[98:99], 1, s[28:29]
	v_add_co_u32_e32 v86, vcc, 0xfe001000, v86
	v_cvt_pk_bf16_f32 v82, v92, v93
	v_cvt_pk_bf16_f32 v83, v90, v91
	v_cvt_pk_bf16_f32 v84, v96, v97
	v_cvt_pk_bf16_f32 v85, v94, v95
	v_addc_co_u32_e32 v87, vcc, -1, v87, vcc
	global_store_dwordx4 v[86:87], v[82:85], off offset:-3840 sc1
	s_cbranch_execz .LBB0_263
	s_branch .LBB0_268

.LBB0_267:
	s_waitcnt vmcnt(0)
	v_pk_add_f32 v[84:85], v[90:91], v[84:85]
	v_pk_add_f32 v[82:83], v[92:93], v[82:83]
	v_pk_add_f32 v[88:89], v[94:95], v[88:89]
	v_pk_add_f32 v[86:87], v[96:97], v[86:87]
	v_cvt_pk_bf16_f32 v82, v82, v83
	v_cvt_pk_bf16_f32 v83, v84, v85
	v_cvt_pk_bf16_f32 v84, v86, v87
	v_cvt_pk_bf16_f32 v85, v88, v89
	global_store_dwordx4 v[100:101], v[82:85], off sc1
.LBB0_268:
	s_nop 1
	v_add_u32_e32 v82, s13, v178
	v_ashrrev_i32_e32 v83, 31, v82
	v_lshlrev_b64 v[82:83], 10, v[82:83]
	v_lshl_add_u64 v[82:83], v[82:83], 0, v[154:155]
	v_pk_mul_f32 v[84:85], v[80:81], v[158:159]
	v_pk_mul_f32 v[86:87], v[78:79], v[160:161]
	v_pk_mul_f32 v[88:89], v[76:77], v[156:157]
	s_and_b64 vcc, exec, s[42:43]
	v_pk_mul_f32 v[90:91], v[74:75], v[152:153]
	s_cbranch_vccnz .LBB0_270
	s_ashr_i32 s28, s12, 2
	s_ashr_i32 s29, s28, 31
	s_lshl_b64 s[28:29], s[28:29], 21
	s_add_u32 s28, s10, s28
	s_addc_u32 s29, s11, s29
	v_lshl_add_u64 v[78:79], v[82:83], 1, s[28:29]
	v_add_co_u32_e32 v78, vcc, 0xfe000000, v78
	v_cvt_pk_bf16_f32 v74, v86, v87
	v_cvt_pk_bf16_f32 v75, v84, v85
	v_cvt_pk_bf16_f32 v76, v90, v91
	v_cvt_pk_bf16_f32 v77, v88, v89
	v_addc_co_u32_e32 v79, vcc, -1, v79, vcc
	global_store_dwordx4 v[78:79], v[74:77], off sc1
	s_cbranch_execz .LBB0_271
	s_branch .LBB0_276

.LBB0_275:
	s_waitcnt vmcnt(0)
	v_pk_add_f32 v[76:77], v[84:85], v[76:77]
	v_pk_add_f32 v[74:75], v[86:87], v[74:75]
	v_pk_add_f32 v[80:81], v[88:89], v[80:81]
	v_pk_add_f32 v[78:79], v[90:91], v[78:79]
	v_cvt_pk_bf16_f32 v74, v74, v75
	v_cvt_pk_bf16_f32 v75, v76, v77
	v_cvt_pk_bf16_f32 v76, v78, v79
	v_cvt_pk_bf16_f32 v77, v80, v81
	global_store_dwordx4 v[92:93], v[74:77], off sc1
.LBB0_276:
	s_nop 1
	v_pk_mul_f32 v[74:75], v[72:73], v[126:127]
	v_pk_mul_f32 v[76:77], v[70:71], v[128:129]
	v_pk_mul_f32 v[78:79], v[68:69], v[124:125]
	s_and_b64 vcc, exec, s[42:43]
	v_pk_mul_f32 v[80:81], v[66:67], v[122:123]
	s_cbranch_vccnz .LBB0_278
	s_ashr_i32 s28, s12, 2
	s_ashr_i32 s29, s28, 31
	s_lshl_b64 s[28:29], s[28:29], 21
	s_add_u32 s28, s10, s28
	s_addc_u32 s29, s11, s29
	v_lshl_add_u64 v[70:71], v[82:83], 1, s[28:29]
	v_add_co_u32_e32 v70, vcc, 0xfe001000, v70
	v_cvt_pk_bf16_f32 v66, v76, v77
	v_cvt_pk_bf16_f32 v67, v74, v75
	v_cvt_pk_bf16_f32 v68, v80, v81
	v_cvt_pk_bf16_f32 v69, v78, v79
	v_addc_co_u32_e32 v71, vcc, -1, v71, vcc
	global_store_dwordx4 v[70:71], v[66:69], off offset:-3840 sc1
	s_cbranch_execz .LBB0_279
	s_branch .LBB0_284

.LBB0_283:
	s_waitcnt vmcnt(0)
	v_pk_add_f32 v[68:69], v[74:75], v[68:69]
	v_pk_add_f32 v[66:67], v[76:77], v[66:67]
	v_pk_add_f32 v[72:73], v[78:79], v[72:73]
	v_pk_add_f32 v[70:71], v[80:81], v[70:71]
	v_cvt_pk_bf16_f32 v66, v66, v67
	v_cvt_pk_bf16_f32 v67, v68, v69
	v_cvt_pk_bf16_f32 v68, v70, v71
	v_cvt_pk_bf16_f32 v69, v72, v73
	global_store_dwordx4 v[84:85], v[66:69], off sc1
.LBB0_284:
	s_nop 1
	v_add_u32_e32 v66, s13, v179
	v_ashrrev_i32_e32 v67, 31, v66
	v_lshlrev_b64 v[66:67], 10, v[66:67]
	v_lshl_add_u64 v[66:67], v[66:67], 0, v[154:155]
	v_pk_mul_f32 v[68:69], v[64:65], v[158:159]
	v_pk_mul_f32 v[70:71], v[62:63], v[160:161]
	v_pk_mul_f32 v[72:73], v[60:61], v[156:157]
	s_and_b64 vcc, exec, s[42:43]
	v_pk_mul_f32 v[74:75], v[58:59], v[152:153]
	s_cbranch_vccnz .LBB0_286
	s_ashr_i32 s28, s12, 2
	s_ashr_i32 s29, s28, 31
	s_lshl_b64 s[28:29], s[28:29], 21
	s_add_u32 s28, s10, s28
	s_addc_u32 s29, s11, s29
	v_lshl_add_u64 v[62:63], v[66:67], 1, s[28:29]
	v_add_co_u32_e32 v62, vcc, 0xfe000000, v62
	v_cvt_pk_bf16_f32 v58, v70, v71
	v_cvt_pk_bf16_f32 v59, v68, v69
	v_cvt_pk_bf16_f32 v60, v74, v75
	v_cvt_pk_bf16_f32 v61, v72, v73
	v_addc_co_u32_e32 v63, vcc, -1, v63, vcc
	global_store_dwordx4 v[62:63], v[58:61], off sc1
	s_cbranch_execz .LBB0_287
	s_branch .LBB0_292

.LBB0_291:
	s_waitcnt vmcnt(0)
	v_pk_add_f32 v[60:61], v[68:69], v[60:61]
	v_pk_add_f32 v[58:59], v[70:71], v[58:59]
	v_pk_add_f32 v[64:65], v[72:73], v[64:65]
	v_pk_add_f32 v[62:63], v[74:75], v[62:63]
	v_cvt_pk_bf16_f32 v58, v58, v59
	v_cvt_pk_bf16_f32 v59, v60, v61
	v_cvt_pk_bf16_f32 v60, v62, v63
	v_cvt_pk_bf16_f32 v61, v64, v65
	global_store_dwordx4 v[76:77], v[58:61], off sc1
.LBB0_292:
	s_nop 1
	v_pk_mul_f32 v[58:59], v[56:57], v[126:127]
	v_pk_mul_f32 v[60:61], v[54:55], v[128:129]
	v_pk_mul_f32 v[62:63], v[52:53], v[124:125]
	s_and_b64 vcc, exec, s[42:43]
	v_pk_mul_f32 v[64:65], v[50:51], v[122:123]
	s_cbranch_vccnz .LBB0_294
	s_ashr_i32 s28, s12, 2
	s_ashr_i32 s29, s28, 31
	s_lshl_b64 s[28:29], s[28:29], 21
	s_add_u32 s28, s10, s28
	s_addc_u32 s29, s11, s29
	v_lshl_add_u64 v[54:55], v[66:67], 1, s[28:29]
	v_add_co_u32_e32 v54, vcc, 0xfe001000, v54
	v_cvt_pk_bf16_f32 v50, v60, v61
	v_cvt_pk_bf16_f32 v51, v58, v59
	v_cvt_pk_bf16_f32 v52, v64, v65
	v_cvt_pk_bf16_f32 v53, v62, v63
	v_addc_co_u32_e32 v55, vcc, -1, v55, vcc
	global_store_dwordx4 v[54:55], v[50:53], off offset:-3840 sc1
	s_cbranch_execz .LBB0_295
	s_branch .LBB0_300

.LBB0_299:
	s_waitcnt vmcnt(0)
	v_pk_add_f32 v[52:53], v[58:59], v[52:53]
	v_pk_add_f32 v[50:51], v[60:61], v[50:51]
	v_pk_add_f32 v[56:57], v[62:63], v[56:57]
	v_pk_add_f32 v[54:55], v[64:65], v[54:55]
	v_cvt_pk_bf16_f32 v50, v50, v51
	v_cvt_pk_bf16_f32 v51, v52, v53
	v_cvt_pk_bf16_f32 v52, v54, v55
	v_cvt_pk_bf16_f32 v53, v56, v57
	global_store_dwordx4 v[68:69], v[50:53], off sc1
.LBB0_300:
	s_nop 1
	v_add_u32_e32 v50, s13, v180
	v_ashrrev_i32_e32 v51, 31, v50
	v_lshlrev_b64 v[50:51], 10, v[50:51]
	v_lshl_add_u64 v[50:51], v[50:51], 0, v[154:155]
	v_pk_mul_f32 v[52:53], v[48:49], v[158:159]
	v_pk_mul_f32 v[54:55], v[46:47], v[160:161]
	v_pk_mul_f32 v[56:57], v[44:45], v[156:157]
	s_and_b64 vcc, exec, s[42:43]
	v_pk_mul_f32 v[58:59], v[42:43], v[152:153]
	s_cbranch_vccnz .LBB0_302
	s_ashr_i32 s28, s12, 2
	s_ashr_i32 s29, s28, 31
	s_lshl_b64 s[28:29], s[28:29], 21
	s_add_u32 s28, s10, s28
	s_addc_u32 s29, s11, s29
	v_lshl_add_u64 v[46:47], v[50:51], 1, s[28:29]
	v_add_co_u32_e32 v46, vcc, 0xfe000000, v46
	v_cvt_pk_bf16_f32 v42, v54, v55
	v_cvt_pk_bf16_f32 v43, v52, v53
	v_cvt_pk_bf16_f32 v44, v58, v59
	v_cvt_pk_bf16_f32 v45, v56, v57
	v_addc_co_u32_e32 v47, vcc, -1, v47, vcc
	global_store_dwordx4 v[46:47], v[42:45], off sc1
	s_cbranch_execz .LBB0_303
	s_branch .LBB0_308

.LBB0_307:
	s_waitcnt vmcnt(0)
	v_pk_add_f32 v[44:45], v[52:53], v[44:45]
	v_pk_add_f32 v[42:43], v[54:55], v[42:43]
	v_pk_add_f32 v[48:49], v[56:57], v[48:49]
	v_pk_add_f32 v[46:47], v[58:59], v[46:47]
	v_cvt_pk_bf16_f32 v42, v42, v43
	v_cvt_pk_bf16_f32 v43, v44, v45
	v_cvt_pk_bf16_f32 v44, v46, v47
	v_cvt_pk_bf16_f32 v45, v48, v49
	global_store_dwordx4 v[60:61], v[42:45], off sc1
.LBB0_308:
	s_nop 1
	v_pk_mul_f32 v[42:43], v[40:41], v[126:127]
	v_pk_mul_f32 v[44:45], v[38:39], v[128:129]
	v_pk_mul_f32 v[46:47], v[36:37], v[124:125]
	s_and_b64 vcc, exec, s[42:43]
	v_pk_mul_f32 v[48:49], v[34:35], v[122:123]
	s_cbranch_vccnz .LBB0_310
	s_ashr_i32 s28, s12, 2
	s_ashr_i32 s29, s28, 31
	s_lshl_b64 s[28:29], s[28:29], 21
	s_add_u32 s28, s10, s28
	s_addc_u32 s29, s11, s29
	v_lshl_add_u64 v[38:39], v[50:51], 1, s[28:29]
	v_add_co_u32_e32 v38, vcc, 0xfe001000, v38
	v_cvt_pk_bf16_f32 v34, v44, v45
	v_cvt_pk_bf16_f32 v35, v42, v43
	v_cvt_pk_bf16_f32 v36, v48, v49
	v_cvt_pk_bf16_f32 v37, v46, v47
	v_addc_co_u32_e32 v39, vcc, -1, v39, vcc
	global_store_dwordx4 v[38:39], v[34:37], off offset:-3840 sc1
	s_cbranch_execz .LBB0_311
	s_branch .LBB0_316

.LBB0_315:
	s_waitcnt vmcnt(0)
	v_pk_add_f32 v[36:37], v[42:43], v[36:37]
	v_pk_add_f32 v[34:35], v[44:45], v[34:35]
	v_pk_add_f32 v[40:41], v[46:47], v[40:41]
	v_pk_add_f32 v[38:39], v[48:49], v[38:39]
	v_cvt_pk_bf16_f32 v34, v34, v35
	v_cvt_pk_bf16_f32 v35, v36, v37
	v_cvt_pk_bf16_f32 v36, v38, v39
	v_cvt_pk_bf16_f32 v37, v40, v41
	global_store_dwordx4 v[52:53], v[34:37], off sc1
.LBB0_316:
	s_nop 1
	v_add_u32_e32 v34, s13, v181
	v_ashrrev_i32_e32 v35, 31, v34
	v_lshlrev_b64 v[34:35], 10, v[34:35]
	v_lshl_add_u64 v[34:35], v[34:35], 0, v[154:155]
	v_pk_mul_f32 v[36:37], v[32:33], v[158:159]
	v_pk_mul_f32 v[38:39], v[30:31], v[160:161]
	v_pk_mul_f32 v[40:41], v[28:29], v[156:157]
	s_and_b64 vcc, exec, s[42:43]
	v_pk_mul_f32 v[42:43], v[26:27], v[152:153]
	s_cbranch_vccnz .LBB0_318
	s_ashr_i32 s28, s12, 2
	s_ashr_i32 s29, s28, 31
	s_lshl_b64 s[28:29], s[28:29], 21
	s_add_u32 s28, s10, s28
	s_addc_u32 s29, s11, s29
	v_lshl_add_u64 v[30:31], v[34:35], 1, s[28:29]
	v_add_co_u32_e32 v30, vcc, 0xfe000000, v30
	v_cvt_pk_bf16_f32 v26, v38, v39
	v_cvt_pk_bf16_f32 v27, v36, v37
	v_cvt_pk_bf16_f32 v28, v42, v43
	v_cvt_pk_bf16_f32 v29, v40, v41
	v_addc_co_u32_e32 v31, vcc, -1, v31, vcc
	global_store_dwordx4 v[30:31], v[26:29], off sc1
	s_cbranch_execz .LBB0_319
	s_branch .LBB0_324

.LBB0_323:
	s_waitcnt vmcnt(0)
	v_pk_add_f32 v[28:29], v[36:37], v[28:29]
	v_pk_add_f32 v[26:27], v[38:39], v[26:27]
	v_pk_add_f32 v[32:33], v[40:41], v[32:33]
	v_pk_add_f32 v[30:31], v[42:43], v[30:31]
	v_cvt_pk_bf16_f32 v26, v26, v27
	v_cvt_pk_bf16_f32 v27, v28, v29
	v_cvt_pk_bf16_f32 v28, v30, v31
	v_cvt_pk_bf16_f32 v29, v32, v33
	global_store_dwordx4 v[44:45], v[26:29], off sc1
.LBB0_324:
	s_nop 1
	v_pk_mul_f32 v[26:27], v[24:25], v[126:127]
	v_pk_mul_f32 v[28:29], v[22:23], v[128:129]
	v_pk_mul_f32 v[30:31], v[20:21], v[124:125]
	s_and_b64 vcc, exec, s[42:43]
	v_pk_mul_f32 v[32:33], v[18:19], v[122:123]
	s_cbranch_vccnz .LBB0_326
	s_ashr_i32 s28, s12, 2
	s_ashr_i32 s29, s28, 31
	s_lshl_b64 s[28:29], s[28:29], 21
	s_add_u32 s28, s10, s28
	s_addc_u32 s29, s11, s29
	v_lshl_add_u64 v[22:23], v[34:35], 1, s[28:29]
	v_add_co_u32_e32 v22, vcc, 0xfe001000, v22
	v_cvt_pk_bf16_f32 v18, v28, v29
	v_cvt_pk_bf16_f32 v19, v26, v27
	v_cvt_pk_bf16_f32 v20, v32, v33
	v_cvt_pk_bf16_f32 v21, v30, v31
	v_addc_co_u32_e32 v23, vcc, -1, v23, vcc
	global_store_dwordx4 v[22:23], v[18:21], off offset:-3840 sc1
	s_cbranch_execz .LBB0_327
	s_branch .LBB0_332

.LBB0_331:
	s_waitcnt vmcnt(0)
	v_pk_add_f32 v[20:21], v[26:27], v[20:21]
	v_pk_add_f32 v[18:19], v[28:29], v[18:19]
	v_pk_add_f32 v[24:25], v[30:31], v[24:25]
	v_pk_add_f32 v[22:23], v[32:33], v[22:23]
	v_cvt_pk_bf16_f32 v18, v18, v19
	v_cvt_pk_bf16_f32 v19, v20, v21
	v_cvt_pk_bf16_f32 v20, v22, v23
	v_cvt_pk_bf16_f32 v21, v24, v25
	global_store_dwordx4 v[36:37], v[18:21], off sc1
.LBB0_332:
	s_nop 1
	v_add_u32_e32 v18, s13, v182
	v_ashrrev_i32_e32 v19, 31, v18
	v_lshlrev_b64 v[18:19], 10, v[18:19]
	v_lshl_add_u64 v[18:19], v[18:19], 0, v[154:155]
	v_pk_mul_f32 v[20:21], v[16:17], v[158:159]
	v_pk_mul_f32 v[22:23], v[14:15], v[160:161]
	v_pk_mul_f32 v[24:25], v[12:13], v[156:157]
	s_and_b64 vcc, exec, s[42:43]
	v_pk_mul_f32 v[26:27], v[10:11], v[152:153]
	s_cbranch_vccnz .LBB0_334
	s_ashr_i32 s28, s12, 2
	s_ashr_i32 s29, s28, 31
	s_lshl_b64 s[28:29], s[28:29], 21
	s_add_u32 s28, s10, s28
	s_addc_u32 s29, s11, s29
	v_lshl_add_u64 v[14:15], v[18:19], 1, s[28:29]
	v_add_co_u32_e32 v14, vcc, 0xfe000000, v14
	v_cvt_pk_bf16_f32 v10, v22, v23
	v_cvt_pk_bf16_f32 v11, v20, v21
	v_cvt_pk_bf16_f32 v12, v26, v27
	v_cvt_pk_bf16_f32 v13, v24, v25
	v_addc_co_u32_e32 v15, vcc, -1, v15, vcc
	global_store_dwordx4 v[14:15], v[10:13], off sc1
	s_cbranch_execz .LBB0_335
	s_branch .LBB0_340

.LBB0_339:
	s_waitcnt vmcnt(0)
	v_pk_add_f32 v[12:13], v[20:21], v[12:13]
	v_pk_add_f32 v[10:11], v[22:23], v[10:11]
	v_pk_add_f32 v[16:17], v[24:25], v[16:17]
	v_pk_add_f32 v[14:15], v[26:27], v[14:15]
	v_cvt_pk_bf16_f32 v10, v10, v11
	v_cvt_pk_bf16_f32 v11, v12, v13
	v_cvt_pk_bf16_f32 v12, v14, v15
	v_cvt_pk_bf16_f32 v13, v16, v17
	global_store_dwordx4 v[28:29], v[10:13], off sc1
.LBB0_340:
	s_nop 1
	v_pk_mul_f32 v[10:11], v[8:9], v[126:127]
	v_pk_mul_f32 v[12:13], v[6:7], v[128:129]
	v_pk_mul_f32 v[14:15], v[4:5], v[124:125]
	s_and_b64 vcc, exec, s[42:43]
	v_pk_mul_f32 v[16:17], v[2:3], v[122:123]
	s_cbranch_vccnz .LBB0_347
	s_ashr_i32 s12, s12, 2
	s_ashr_i32 s13, s12, 31
	s_lshl_b64 s[12:13], s[12:13], 21
	s_add_u32 s12, s10, s12
	s_addc_u32 s13, s11, s13
	v_lshl_add_u64 v[6:7], v[18:19], 1, s[12:13]
	v_add_co_u32_e32 v6, vcc, 0xfe001000, v6
	v_cvt_pk_bf16_f32 v2, v12, v13
	v_cvt_pk_bf16_f32 v3, v10, v11
	v_cvt_pk_bf16_f32 v4, v16, v17
	v_cvt_pk_bf16_f32 v5, v14, v15
	v_addc_co_u32_e32 v7, vcc, -1, v7, vcc
	global_store_dwordx4 v[6:7], v[2:5], off offset:-3840 sc1
	s_cbranch_execnz .LBB0_348

.LBB0_346:
	s_waitcnt vmcnt(0)
	v_pk_add_f32 v[4:5], v[10:11], v[4:5]
	v_pk_add_f32 v[2:3], v[12:13], v[2:3]
	v_pk_add_f32 v[8:9], v[14:15], v[8:9]
	v_pk_add_f32 v[6:7], v[16:17], v[6:7]
	v_cvt_pk_bf16_f32 v2, v2, v3
	v_cvt_pk_bf16_f32 v3, v4, v5
	v_cvt_pk_bf16_f32 v4, v6, v7
	v_cvt_pk_bf16_f32 v5, v8, v9
	global_store_dwordx4 v[20:21], v[2:5], off sc1
	s_and_b64 vcc, exec, s[38:39]
	s_mov_b64 s[12:13], -1
	s_cbranch_vccnz .LBB0_204
	s_branch .LBB0_349

.LBB0_377:
	v_mul_f32_e32 v149, 0xbfb8aa3b, v122
	v_exp_f32_e32 v149, v149
	v_pk_mul_f32 v[128:129], v[128:129], v[124:125]
	v_pk_mul_f32 v[120:121], v[120:121], v[116:117]
	v_pk_mul_f32 v[112:113], v[112:113], v[108:109]
	v_add_f32_e32 v149, 1.0, v149
	v_rcp_f32_e32 v152, v149
	v_mul_f32_e32 v149, 0xbfb8aa3b, v123
	v_exp_f32_e32 v149, v149
	v_pk_mul_f32 v[122:123], v[126:127], v[122:123]
	v_pk_mul_f32 v[104:105], v[104:105], v[100:101]
	v_pk_mul_f32 v[96:97], v[96:97], v[92:93]
	v_add_f32_e32 v149, 1.0, v149
	v_rcp_f32_e32 v153, v149
	v_pk_mul_f32 v[88:89], v[88:89], v[84:85]
	v_pk_mul_f32 v[80:81], v[80:81], v[76:77]
	v_pk_mul_f32 v[72:73], v[72:73], v[68:69]
	v_pk_mul_f32 v[122:123], v[122:123], v[152:153]
	v_pk_mul_f32 v[64:65], v[64:65], v[60:61]
	v_cvt_pk_bf16_f32 v122, v122, v123
	v_mul_f32_e32 v123, 0xbfb8aa3b, v124
	v_exp_f32_e32 v123, v123
	v_pk_mul_f32 v[56:57], v[56:57], v[52:53]
	v_pk_mul_f32 v[48:49], v[48:49], v[44:45]
	v_pk_mul_f32 v[40:41], v[40:41], v[36:37]
	v_add_f32_e32 v123, 1.0, v123
	v_rcp_f32_e32 v124, v123
	v_mul_f32_e32 v123, 0xbfb8aa3b, v125
	v_exp_f32_e32 v123, v123
	v_pk_mul_f32 v[32:33], v[32:33], v[28:29]
	v_pk_mul_f32 v[24:25], v[24:25], v[20:21]
	v_pk_mul_f32 v[16:17], v[16:17], v[12:13]
	v_add_f32_e32 v123, 1.0, v123
	v_rcp_f32_e32 v125, v123
	v_pk_mul_f32 v[2:3], v[2:3], v[6:7]
	v_lshl_add_u32 v148, s26, 8, v144
	v_lshl_or_b32 v142, s24, 7, v146
	v_pk_mul_f32 v[124:125], v[128:129], v[124:125]
	v_ashrrev_i32_e32 v143, 31, v142
	v_cvt_pk_bf16_f32 v123, v124, v125
	v_mul_f32_e32 v124, 0xbfb8aa3b, v114
	v_mul_f32_e32 v125, 0xbfb8aa3b, v115
	v_exp_f32_e32 v124, v124
	v_exp_f32_e32 v125, v125
	v_pk_mul_f32 v[114:115], v[118:119], v[114:115]
	v_mov_b64_e32 v[140:141], s[6:7]
	v_add_f32_e32 v124, 1.0, v124
	v_add_f32_e32 v125, 1.0, v125
	v_rcp_f32_e32 v124, v124
	v_rcp_f32_e32 v125, v125
	v_pk_mul_f32 v[4:5], v[4:5], v[8:9]
	v_mad_i64_i32 v[150:151], s[24:25], v148, s86, v[140:141]
	v_pk_mul_f32 v[114:115], v[114:115], v[124:125]
	v_lshlrev_b64 v[142:143], 1, v[142:143]
	v_cvt_pk_bf16_f32 v124, v114, v115
	v_mul_f32_e32 v114, 0xbfb8aa3b, v116
	v_mul_f32_e32 v115, 0xbfb8aa3b, v117
	v_mul_f32_e32 v116, 0xbfb8aa3b, v106
	v_mul_f32_e32 v117, 0xbfb8aa3b, v107
	v_exp_f32_e32 v116, v116
	v_exp_f32_e32 v117, v117
	v_pk_mul_f32 v[106:107], v[110:111], v[106:107]
	v_exp_f32_e32 v114, v114
	v_add_f32_e32 v116, 1.0, v116
	v_add_f32_e32 v117, 1.0, v117
	v_rcp_f32_e32 v116, v116
	v_rcp_f32_e32 v117, v117
	v_exp_f32_e32 v115, v115
	v_add_f32_e32 v114, 1.0, v114
	v_rcp_f32_e32 v114, v114
	v_pk_mul_f32 v[106:107], v[106:107], v[116:117]
	v_add_f32_e32 v115, 1.0, v115
	v_cvt_pk_bf16_f32 v106, v106, v107
	v_mul_f32_e32 v107, 0xbfb8aa3b, v108
	v_exp_f32_e32 v107, v107
	v_rcp_f32_e32 v115, v115
	v_lshl_add_u64 v[150:151], v[150:151], 0, v[142:143]
	s_andn2_b64 vcc, exec, s[18:19]
	v_add_f32_e32 v107, 1.0, v107
	v_rcp_f32_e32 v108, v107
	v_mul_f32_e32 v107, 0xbfb8aa3b, v109
	v_exp_f32_e32 v107, v107
	v_pk_mul_f32 v[114:115], v[120:121], v[114:115]
	v_add_f32_e32 v107, 1.0, v107
	v_rcp_f32_e32 v109, v107
	v_cvt_pk_bf16_f32 v125, v114, v115
	v_or_b32_e32 v114, 16, v148
	v_mad_i64_i32 v[114:115], s[24:25], v114, s86, v[140:141]
	v_pk_mul_f32 v[108:109], v[112:113], v[108:109]
	v_lshl_add_u64 v[114:115], v[114:115], 0, v[142:143]
	v_cvt_pk_bf16_f32 v107, v108, v109
	v_mul_f32_e32 v108, 0xbfb8aa3b, v98
	v_mul_f32_e32 v109, 0xbfb8aa3b, v99
	v_exp_f32_e32 v108, v108
	v_exp_f32_e32 v109, v109
	v_pk_mul_f32 v[98:99], v[102:103], v[98:99]
	global_store_dwordx4 v[150:151], v[122:125], off sc1
	v_add_f32_e32 v108, 1.0, v108
	v_add_f32_e32 v109, 1.0, v109
	v_rcp_f32_e32 v108, v108
	v_rcp_f32_e32 v109, v109
	s_nop 0
	v_pk_mul_f32 v[98:99], v[98:99], v[108:109]
	s_nop 0
	v_cvt_pk_bf16_f32 v108, v98, v99
	v_mul_f32_e32 v98, 0xbfb8aa3b, v100
	v_mul_f32_e32 v99, 0xbfb8aa3b, v101
	v_mul_f32_e32 v100, 0xbfb8aa3b, v90
	v_mul_f32_e32 v101, 0xbfb8aa3b, v91
	v_exp_f32_e32 v100, v100
	v_exp_f32_e32 v101, v101
	v_pk_mul_f32 v[90:91], v[94:95], v[90:91]
	v_exp_f32_e32 v98, v98
	v_add_f32_e32 v100, 1.0, v100
	v_add_f32_e32 v101, 1.0, v101
	v_rcp_f32_e32 v100, v100
	v_rcp_f32_e32 v101, v101
	v_exp_f32_e32 v99, v99
	v_add_f32_e32 v98, 1.0, v98
	v_rcp_f32_e32 v98, v98
	v_pk_mul_f32 v[90:91], v[90:91], v[100:101]
	v_add_f32_e32 v99, 1.0, v99
	v_cvt_pk_bf16_f32 v90, v90, v91
	v_mul_f32_e32 v91, 0xbfb8aa3b, v92
	v_exp_f32_e32 v91, v91
	v_rcp_f32_e32 v99, v99
	v_add_f32_e32 v91, 1.0, v91
	v_rcp_f32_e32 v92, v91
	v_mul_f32_e32 v91, 0xbfb8aa3b, v93
	v_exp_f32_e32 v91, v91
	v_pk_mul_f32 v[98:99], v[104:105], v[98:99]
	v_add_f32_e32 v91, 1.0, v91
	v_rcp_f32_e32 v93, v91
	v_cvt_pk_bf16_f32 v109, v98, v99
	v_or_b32_e32 v98, 32, v148
	v_mad_i64_i32 v[98:99], s[24:25], v98, s86, v[140:141]
	v_pk_mul_f32 v[92:93], v[96:97], v[92:93]
	v_lshl_add_u64 v[98:99], v[98:99], 0, v[142:143]
	v_cvt_pk_bf16_f32 v91, v92, v93
	v_mul_f32_e32 v92, 0xbfb8aa3b, v82
	v_mul_f32_e32 v93, 0xbfb8aa3b, v83
	v_exp_f32_e32 v92, v92
	v_exp_f32_e32 v93, v93
	v_pk_mul_f32 v[82:83], v[86:87], v[82:83]
	global_store_dwordx4 v[114:115], v[106:109], off sc1
	v_add_f32_e32 v92, 1.0, v92
	v_add_f32_e32 v93, 1.0, v93
	v_rcp_f32_e32 v92, v92
	v_rcp_f32_e32 v93, v93
	s_nop 0
	v_pk_mul_f32 v[82:83], v[82:83], v[92:93]
	s_nop 0
	v_cvt_pk_bf16_f32 v92, v82, v83
	v_mul_f32_e32 v82, 0xbfb8aa3b, v84
	v_mul_f32_e32 v83, 0xbfb8aa3b, v85
	v_mul_f32_e32 v84, 0xbfb8aa3b, v74
	v_mul_f32_e32 v85, 0xbfb8aa3b, v75
	v_exp_f32_e32 v84, v84
	v_exp_f32_e32 v85, v85
	v_pk_mul_f32 v[74:75], v[78:79], v[74:75]
	v_exp_f32_e32 v82, v82
	v_add_f32_e32 v84, 1.0, v84
	v_add_f32_e32 v85, 1.0, v85
	v_rcp_f32_e32 v84, v84
	v_rcp_f32_e32 v85, v85
	v_exp_f32_e32 v83, v83
	v_add_f32_e32 v82, 1.0, v82
	v_rcp_f32_e32 v82, v82
	v_pk_mul_f32 v[74:75], v[74:75], v[84:85]
	v_add_f32_e32 v83, 1.0, v83
	v_cvt_pk_bf16_f32 v74, v74, v75
	v_mul_f32_e32 v75, 0xbfb8aa3b, v76
	v_exp_f32_e32 v75, v75
	v_rcp_f32_e32 v83, v83
	v_add_f32_e32 v75, 1.0, v75
	v_rcp_f32_e32 v76, v75
	v_mul_f32_e32 v75, 0xbfb8aa3b, v77
	v_exp_f32_e32 v75, v75
	v_pk_mul_f32 v[82:83], v[88:89], v[82:83]
	v_add_f32_e32 v75, 1.0, v75
	v_rcp_f32_e32 v77, v75
	v_cvt_pk_bf16_f32 v93, v82, v83
	v_or_b32_e32 v82, 48, v148
	v_mad_i64_i32 v[82:83], s[24:25], v82, s86, v[140:141]
	v_pk_mul_f32 v[76:77], v[80:81], v[76:77]
	v_lshl_add_u64 v[82:83], v[82:83], 0, v[142:143]
	v_cvt_pk_bf16_f32 v75, v76, v77
	v_mul_f32_e32 v76, 0xbfb8aa3b, v66
	v_mul_f32_e32 v77, 0xbfb8aa3b, v67
	v_exp_f32_e32 v76, v76
	v_exp_f32_e32 v77, v77
	v_pk_mul_f32 v[66:67], v[70:71], v[66:67]
	global_store_dwordx4 v[98:99], v[90:93], off sc1
	v_add_f32_e32 v76, 1.0, v76
	v_add_f32_e32 v77, 1.0, v77
	v_rcp_f32_e32 v76, v76
	v_rcp_f32_e32 v77, v77
	s_nop 0
	v_pk_mul_f32 v[66:67], v[66:67], v[76:77]
	s_nop 0
	v_cvt_pk_bf16_f32 v76, v66, v67
	v_mul_f32_e32 v66, 0xbfb8aa3b, v68
	v_mul_f32_e32 v67, 0xbfb8aa3b, v69
	v_mul_f32_e32 v68, 0xbfb8aa3b, v58
	v_mul_f32_e32 v69, 0xbfb8aa3b, v59
	v_exp_f32_e32 v68, v68
	v_exp_f32_e32 v69, v69
	v_pk_mul_f32 v[58:59], v[62:63], v[58:59]
	v_exp_f32_e32 v66, v66
	v_add_f32_e32 v68, 1.0, v68
	v_add_f32_e32 v69, 1.0, v69
	v_rcp_f32_e32 v68, v68
	v_rcp_f32_e32 v69, v69
	v_exp_f32_e32 v67, v67
	v_add_f32_e32 v66, 1.0, v66
	v_rcp_f32_e32 v66, v66
	v_pk_mul_f32 v[58:59], v[58:59], v[68:69]
	v_add_f32_e32 v67, 1.0, v67
	v_cvt_pk_bf16_f32 v58, v58, v59
	v_mul_f32_e32 v59, 0xbfb8aa3b, v60
	v_exp_f32_e32 v59, v59
	v_rcp_f32_e32 v67, v67
	v_add_f32_e32 v59, 1.0, v59
	v_rcp_f32_e32 v60, v59
	v_mul_f32_e32 v59, 0xbfb8aa3b, v61
	v_exp_f32_e32 v59, v59
	v_pk_mul_f32 v[66:67], v[72:73], v[66:67]
	v_add_f32_e32 v59, 1.0, v59
	v_rcp_f32_e32 v61, v59
	v_cvt_pk_bf16_f32 v77, v66, v67
	v_add_u32_e32 v66, 0x80, v148
	v_mad_i64_i32 v[66:67], s[24:25], v66, s86, v[140:141]
	v_pk_mul_f32 v[60:61], v[64:65], v[60:61]
	v_lshl_add_u64 v[66:67], v[66:67], 0, v[142:143]
	v_cvt_pk_bf16_f32 v59, v60, v61
	v_mul_f32_e32 v60, 0xbfb8aa3b, v50
	v_mul_f32_e32 v61, 0xbfb8aa3b, v51
	v_exp_f32_e32 v60, v60
	v_exp_f32_e32 v61, v61
	v_pk_mul_f32 v[50:51], v[54:55], v[50:51]
	global_store_dwordx4 v[82:83], v[74:77], off sc1
	v_add_f32_e32 v60, 1.0, v60
	v_add_f32_e32 v61, 1.0, v61
	v_rcp_f32_e32 v60, v60
	v_rcp_f32_e32 v61, v61
	s_nop 0
	v_pk_mul_f32 v[50:51], v[50:51], v[60:61]
	s_nop 0
	v_cvt_pk_bf16_f32 v60, v50, v51
	v_mul_f32_e32 v50, 0xbfb8aa3b, v52
	v_mul_f32_e32 v51, 0xbfb8aa3b, v53
	v_mul_f32_e32 v52, 0xbfb8aa3b, v42
	v_mul_f32_e32 v53, 0xbfb8aa3b, v43
	v_exp_f32_e32 v52, v52
	v_exp_f32_e32 v53, v53
	v_pk_mul_f32 v[42:43], v[46:47], v[42:43]
	v_exp_f32_e32 v50, v50
	v_add_f32_e32 v52, 1.0, v52
	v_add_f32_e32 v53, 1.0, v53
	v_rcp_f32_e32 v52, v52
	v_rcp_f32_e32 v53, v53
	v_exp_f32_e32 v51, v51
	v_add_f32_e32 v50, 1.0, v50
	v_rcp_f32_e32 v50, v50
	v_pk_mul_f32 v[42:43], v[42:43], v[52:53]
	v_add_f32_e32 v51, 1.0, v51
	v_cvt_pk_bf16_f32 v42, v42, v43
	v_mul_f32_e32 v43, 0xbfb8aa3b, v44
	v_exp_f32_e32 v43, v43
	v_rcp_f32_e32 v51, v51
	v_add_f32_e32 v43, 1.0, v43
	v_rcp_f32_e32 v44, v43
	v_mul_f32_e32 v43, 0xbfb8aa3b, v45
	v_exp_f32_e32 v43, v43
	v_pk_mul_f32 v[50:51], v[56:57], v[50:51]
	v_add_f32_e32 v43, 1.0, v43
	v_rcp_f32_e32 v45, v43
	v_cvt_pk_bf16_f32 v61, v50, v51
	v_add_u32_e32 v50, 0x90, v148
	v_mad_i64_i32 v[50:51], s[24:25], v50, s86, v[140:141]
	v_pk_mul_f32 v[44:45], v[48:49], v[44:45]
	v_lshl_add_u64 v[50:51], v[50:51], 0, v[142:143]
	v_cvt_pk_bf16_f32 v43, v44, v45
	v_mul_f32_e32 v44, 0xbfb8aa3b, v34
	v_mul_f32_e32 v45, 0xbfb8aa3b, v35
	v_exp_f32_e32 v44, v44
	v_exp_f32_e32 v45, v45
	v_pk_mul_f32 v[34:35], v[38:39], v[34:35]
	global_store_dwordx4 v[66:67], v[58:61], off sc1
	v_add_f32_e32 v44, 1.0, v44
	v_add_f32_e32 v45, 1.0, v45
	v_rcp_f32_e32 v44, v44
	v_rcp_f32_e32 v45, v45
	s_nop 0
	v_pk_mul_f32 v[34:35], v[34:35], v[44:45]
	s_nop 0
	v_cvt_pk_bf16_f32 v44, v34, v35
	v_mul_f32_e32 v34, 0xbfb8aa3b, v36
	v_mul_f32_e32 v35, 0xbfb8aa3b, v37
	v_mul_f32_e32 v36, 0xbfb8aa3b, v26
	v_mul_f32_e32 v37, 0xbfb8aa3b, v27
	v_exp_f32_e32 v36, v36
	v_exp_f32_e32 v37, v37
	v_pk_mul_f32 v[26:27], v[30:31], v[26:27]
	v_exp_f32_e32 v34, v34
	v_add_f32_e32 v36, 1.0, v36
	v_add_f32_e32 v37, 1.0, v37
	v_rcp_f32_e32 v36, v36
	v_rcp_f32_e32 v37, v37
	v_exp_f32_e32 v35, v35
	v_add_f32_e32 v34, 1.0, v34
	v_rcp_f32_e32 v34, v34
	v_pk_mul_f32 v[26:27], v[26:27], v[36:37]
	v_add_f32_e32 v35, 1.0, v35
	v_cvt_pk_bf16_f32 v26, v26, v27
	v_mul_f32_e32 v27, 0xbfb8aa3b, v28
	v_exp_f32_e32 v27, v27
	v_rcp_f32_e32 v35, v35
	v_add_f32_e32 v27, 1.0, v27
	v_rcp_f32_e32 v28, v27
	v_mul_f32_e32 v27, 0xbfb8aa3b, v29
	v_exp_f32_e32 v27, v27
	v_pk_mul_f32 v[34:35], v[40:41], v[34:35]
	v_add_f32_e32 v27, 1.0, v27
	v_rcp_f32_e32 v29, v27
	v_cvt_pk_bf16_f32 v45, v34, v35
	v_add_u32_e32 v34, 0xa0, v148
	v_mad_i64_i32 v[34:35], s[24:25], v34, s86, v[140:141]
	v_pk_mul_f32 v[28:29], v[32:33], v[28:29]
	v_lshl_add_u64 v[34:35], v[34:35], 0, v[142:143]
	v_cvt_pk_bf16_f32 v27, v28, v29
	v_mul_f32_e32 v28, 0xbfb8aa3b, v18
	v_mul_f32_e32 v29, 0xbfb8aa3b, v19
	v_exp_f32_e32 v28, v28
	v_exp_f32_e32 v29, v29
	v_pk_mul_f32 v[18:19], v[22:23], v[18:19]
	global_store_dwordx4 v[50:51], v[42:45], off sc1
	v_add_f32_e32 v28, 1.0, v28
	v_add_f32_e32 v29, 1.0, v29
	v_rcp_f32_e32 v28, v28
	v_rcp_f32_e32 v29, v29
	s_nop 0
	v_pk_mul_f32 v[18:19], v[18:19], v[28:29]
	s_nop 0
	v_cvt_pk_bf16_f32 v28, v18, v19
	v_mul_f32_e32 v18, 0xbfb8aa3b, v20
	v_mul_f32_e32 v19, 0xbfb8aa3b, v21
	v_mul_f32_e32 v20, 0xbfb8aa3b, v10
	v_mul_f32_e32 v21, 0xbfb8aa3b, v11
	v_exp_f32_e32 v20, v20
	v_exp_f32_e32 v21, v21
	v_pk_mul_f32 v[10:11], v[14:15], v[10:11]
	v_exp_f32_e32 v18, v18
	v_add_f32_e32 v20, 1.0, v20
	v_add_f32_e32 v21, 1.0, v21
	v_rcp_f32_e32 v20, v20
	v_rcp_f32_e32 v21, v21
	v_exp_f32_e32 v19, v19
	v_add_f32_e32 v18, 1.0, v18
	v_rcp_f32_e32 v18, v18
	v_pk_mul_f32 v[10:11], v[10:11], v[20:21]
	v_add_f32_e32 v19, 1.0, v19
	v_cvt_pk_bf16_f32 v10, v10, v11
	v_mul_f32_e32 v11, 0xbfb8aa3b, v12
	v_exp_f32_e32 v11, v11
	v_rcp_f32_e32 v19, v19
	v_add_f32_e32 v11, 1.0, v11
	v_rcp_f32_e32 v12, v11
	v_mul_f32_e32 v11, 0xbfb8aa3b, v13
	v_exp_f32_e32 v11, v11
	v_pk_mul_f32 v[18:19], v[24:25], v[18:19]
	v_add_f32_e32 v11, 1.0, v11
	v_rcp_f32_e32 v13, v11
	v_cvt_pk_bf16_f32 v29, v18, v19
	v_add_u32_e32 v18, 0xb0, v148
	v_mad_i64_i32 v[18:19], s[24:25], v18, s86, v[140:141]
	v_pk_mul_f32 v[12:13], v[16:17], v[12:13]
	v_lshl_add_u64 v[18:19], v[18:19], 0, v[142:143]
	v_cvt_pk_bf16_f32 v11, v12, v13
	v_mul_f32_e32 v12, 0xbfb8aa3b, v6
	v_mul_f32_e32 v13, 0xbfb8aa3b, v7
	v_exp_f32_e32 v12, v12
	v_exp_f32_e32 v13, v13
	s_mov_b64 s[24:25], -1
	global_store_dwordx4 v[34:35], v[26:29], off sc1
	v_add_f32_e32 v12, 1.0, v12
	v_add_f32_e32 v13, 1.0, v13
	v_rcp_f32_e32 v12, v12
	v_rcp_f32_e32 v13, v13
	s_nop 0
	v_pk_mul_f32 v[2:3], v[2:3], v[12:13]
	s_nop 0
	v_cvt_pk_bf16_f32 v12, v2, v3
	v_mul_f32_e32 v2, 0xbfb8aa3b, v8
	v_mul_f32_e32 v3, 0xbfb8aa3b, v9
	v_exp_f32_e32 v2, v2
	v_exp_f32_e32 v3, v3
	v_add_f32_e32 v2, 1.0, v2
	v_add_f32_e32 v3, 1.0, v3
	v_rcp_f32_e32 v2, v2
	v_rcp_f32_e32 v3, v3
	s_nop 0
	v_pk_mul_f32 v[2:3], v[4:5], v[2:3]
	s_nop 0
	v_cvt_pk_bf16_f32 v13, v2, v3
	global_store_dwordx4 v[18:19], v[10:13], off sc1
	s_cbranch_vccnz .LBB0_367
	s_andn2_b64 vcc, exec, s[4:5]
	s_cbranch_vccnz .LBB0_366
	s_barrier
	s_branch .LBB0_366

.LBB0_584:
	s_ashr_i32 s17, s20, 6
	s_add_i32 s17, s17, s92
	v_readlane_b32 s18, v249, 49
	s_mul_i32 s19, s18, s17
	s_add_i32 s18, s19, s18
	s_min_i32 s23, s19, 0x4000
	s_cmp_lt_i32 s18, s23
	s_cbranch_scc1 .LBB0_605
	s_min_i32 s22, s18, 0x4000
	s_and_b64 s[6:7], s[6:7], exec
	s_movk_i32 s6, 0xc00
	s_cselect_b32 s18, s6, 0x1800
	s_and_b64 s[6:7], s[28:29], exec
	s_cselect_b32 s6, 0x2d000, 0
	s_waitcnt lgkmcnt(0)
	s_add_u32 s6, s8, s6
	s_addc_u32 s7, s9, 0
	s_and_b64 s[4:5], s[4:5], exec
	s_cselect_b32 s4, 0, s18
	s_lshl_b32 s4, s4, 2
	s_add_u32 s18, s6, s4
	s_addc_u32 s19, s7, 0
	s_and_b64 s[4:5], s[28:29], exec
	s_cselect_b32 s4, 0x1000, 0
	s_cmp_eq_u32 s3, 17
	s_movk_i32 s5, 0x4400
	s_cselect_b32 s24, 0x4000, s5
	s_add_i32 s6, s24, 0xffffc000
	s_add_u32 s14, s14, s4
	s_addc_u32 s15, s15, 0
	s_add_i32 s25, s17, 0x4000
	v_lshlrev_b32_e32 v0, 2, v2
	s_cmp_lg_u64 s[10:11], 0
	v_and_b32_e32 v3, 0xfc, v0
	s_cselect_b64 s[4:5], -1, 0
	s_cmp_lg_u32 s16, 0
	v_lshlrev_b32_e32 v0, 1, v3
	s_cselect_b64 s[20:21], -1, 0
	s_cmp_lt_i32 s17, s6
	v_lshl_add_u64 v[4:5], s[8:9], 0, v[0:1]
	v_lshl_add_u64 v[58:59], s[12:13], 0, v[0:1]
	v_and_b32_e32 v0, 63, v2
	s_cselect_b64 s[6:7], -1, 0
	s_mov_b64 s[8:9], 0x9000000
	s_and_b32 s26, s16, 3
	v_lshlrev_b32_e32 v0, 3, v0
	v_lshl_add_u64 v[50:51], v[4:5], 0, s[8:9]
	v_lshlrev_b32_e32 v6, 2, v3
	v_mov_b32_e32 v7, v1
	s_mov_b64 s[8:9], 0x4c00000
	s_cmp_gt_u32 s16, 3
	v_lshl_add_u64 v[2:3], s[12:13], 0, v[0:1]
	s_mov_b64 s[12:13], 0x400
	v_lshl_add_u64 v[52:53], s[14:15], 0, v[6:7]
	v_lshl_add_u64 v[54:55], v[4:5], 0, s[8:9]
	v_lshl_add_u64 v[56:57], s[10:11], 0, v[6:7]
	s_cselect_b64 s[8:9], -1, 0
	s_cmp_lg_u32 s26, 0
	v_lshl_add_u64 v[60:61], s[18:19], 0, v[6:7]
	s_mov_b64 s[14:15], 0x1000
	v_lshl_add_u64 v[64:65], v[2:3], 0, s[12:13]
	v_mov_b32_e32 v2, v1
	v_mov_b32_e32 v3, v1
	v_mov_b32_e32 v4, v1
	v_mov_b32_e32 v5, v1
	v_mov_b32_e32 v6, v1
	v_mov_b32_e32 v8, v1
	v_mov_b32_e32 v9, v1
	v_mov_b32_e32 v10, v1
	v_mov_b32_e32 v11, v1
	v_mov_b32_e32 v12, v1
	v_mov_b32_e32 v13, v1
	v_mov_b32_e32 v14, v1
	v_mov_b32_e32 v15, v1
	s_cselect_b64 s[10:11], -1, 0
	v_lshl_add_u64 v[62:63], v[60:61], 0, s[14:15]
	s_lshl_b32 s14, s16, 21
	v_mov_b32_e32 v0, v1
	v_mov_b64_e32 v[16:17], v[14:15]
	s_and_b32 s27, s14, 0x1800000
	s_mov_b32 s28, -1
	s_xor_b64 s[12:13], s[20:21], -1
	v_mov_b64_e32 v[14:15], v[12:13]
	v_mov_b64_e32 v[12:13], v[10:11]
	v_mov_b64_e32 v[10:11], v[8:9]
	v_mov_b64_e32 v[8:9], v[6:7]
	v_mov_b64_e32 v[6:7], v[4:5]
	v_mov_b64_e32 v[4:5], v[2:3]
	v_mov_b64_e32 v[2:3], v[0:1]
	s_and_b64 vcc, exec, s[4:5]
	s_cbranch_vccnz .Lnf_skip
	s_sub_i32 vcc_lo, s22, s23
	s_cmp_lg_u32 vcc_lo, 8
	s_cbranch_scc1 .Lnf_skip
	s_lshr_b32 vcc_lo, s23, 12
	s_add_i32 vcc_hi, s22, -1
	s_lshr_b32 vcc_hi, vcc_hi, 12
	s_cmp_lg_u32 vcc_lo, vcc_hi
	s_cbranch_scc1 .Lnf_skip
	s_mul_i32 vcc_lo, vcc_lo, 0x9000
	s_mov_b32 vcc_hi, 0
	v_and_b32_e32 v114, 63, v224
	v_mov_b32_e32 v115, 0
	v_mov_b32_e32 v117, 0
	v_lshlrev_b32_e32 v116, 4, v114
	v_lshlrev_b32_e32 v114, 3, v114
	v_lshl_add_u64 v[118:119], v[52:53], 0, v[116:117]
	v_lshl_add_u64 v[120:121], v[62:63], 0, v[116:117]
	v_lshl_add_u64 v[194:195], v[60:61], 0, v[116:117]
	v_lshl_add_u64 v[120:121], v[120:121], 0, vcc
	v_lshl_add_u64 v[194:195], v[194:195], 0, vcc
	global_load_dwordx4 v[66:69], v[118:119], off
	global_load_dwordx4 v[70:73], v[118:119], off offset:16
	global_load_dwordx4 v[74:77], v[118:119], off offset:2048
	global_load_dwordx4 v[78:81], v[118:119], off offset:2064
	global_load_dwordx4 v[82:85], v[120:121], off
	global_load_dwordx4 v[86:89], v[120:121], off offset:16
	global_load_dwordx4 v[90:93], v[120:121], off offset:2048
	global_load_dwordx4 v[94:97], v[120:121], off offset:2064
	global_load_dwordx4 v[98:101], v[194:195], off
	global_load_dwordx4 v[102:105], v[194:195], off offset:16
	global_load_dwordx4 v[106:109], v[194:195], off offset:2048
	global_load_dwordx4 v[110:113], v[194:195], off offset:2064
	s_mov_b32 vcc_lo, s23
	s_lshl_b64 vcc, vcc, 11
	v_lshl_add_u64 v[186:187], v[54:55], 0, v[114:115]
	v_lshl_add_u64 v[186:187], v[186:187], 0, vcc
	s_mov_b64 vcc, 0x1000
	v_lshl_add_u64 v[188:189], v[186:187], 0, vcc
	v_lshl_add_u64 v[190:191], v[188:189], 0, vcc
	v_lshl_add_u64 v[192:193], v[190:191], 0, vcc
	global_load_dwordx4 v[122:125], v[186:187], off
	global_load_dwordx4 v[126:129], v[186:187], off offset:1024
	global_load_dwordx4 v[130:133], v[186:187], off offset:2048
	global_load_dwordx4 v[134:137], v[186:187], off offset:3072
	global_load_dwordx4 v[138:141], v[188:189], off
	global_load_dwordx4 v[142:145], v[188:189], off offset:1024
	global_load_dwordx4 v[146:149], v[188:189], off offset:2048
	global_load_dwordx4 v[150:153], v[188:189], off offset:3072
	global_load_dwordx4 v[154:157], v[190:191], off
	global_load_dwordx4 v[158:161], v[190:191], off offset:1024
	global_load_dwordx4 v[162:165], v[190:191], off offset:2048
	global_load_dwordx4 v[166:169], v[190:191], off offset:3072
	global_load_dwordx4 v[170:173], v[192:193], off
	global_load_dwordx4 v[174:177], v[192:193], off offset:1024
	global_load_dwordx4 v[178:181], v[192:193], off offset:2048
	global_load_dwordx4 v[182:185], v[192:193], off offset:3072
	v_mov_b32_e32 v220, 0x3a800000
	v_mov_b32_e32 v221, 0x358637bd
	s_mov_b64 vcc, 0x4400000
	v_lshl_add_u64 v[186:187], v[186:187], 0, vcc
	v_lshl_add_u64 v[188:189], v[188:189], 0, vcc
	v_lshl_add_u64 v[190:191], v[190:191], 0, vcc
	v_lshl_add_u64 v[192:193], v[192:193], 0, vcc
	s_waitcnt vmcnt(16)
	v_pk_add_f32 v[82:83], v[82:83], 1.0 op_sel_hi:[1,0]
	v_pk_add_f32 v[84:85], v[84:85], 1.0 op_sel_hi:[1,0]
	v_pk_add_f32 v[86:87], v[86:87], 1.0 op_sel_hi:[1,0]
	v_pk_add_f32 v[88:89], v[88:89], 1.0 op_sel_hi:[1,0]
	v_pk_add_f32 v[90:91], v[90:91], 1.0 op_sel_hi:[1,0]
	v_pk_add_f32 v[92:93], v[92:93], 1.0 op_sel_hi:[1,0]
	v_pk_add_f32 v[94:95], v[94:95], 1.0 op_sel_hi:[1,0]
	v_pk_add_f32 v[96:97], v[96:97], 1.0 op_sel_hi:[1,0]
	v_pk_mul_f32 v[66:67], v[66:67], v[82:83]
	v_pk_mul_f32 v[68:69], v[68:69], v[84:85]
	v_pk_mul_f32 v[70:71], v[70:71], v[86:87]
	v_pk_mul_f32 v[72:73], v[72:73], v[88:89]
	v_pk_mul_f32 v[74:75], v[74:75], v[90:91]
	v_pk_mul_f32 v[76:77], v[76:77], v[92:93]
	v_pk_mul_f32 v[78:79], v[78:79], v[94:95]
	v_pk_mul_f32 v[80:81], v[80:81], v[96:97]
	s_waitcnt vmcnt(14)
	v_lshlrev_b32_e32 v212, 16, v122
	v_and_b32_e32 v213, 0xffff0000, v122
	v_mul_f32_e32 v82, v212, v212
	v_mul_f32_e32 v83, v213, v213
	v_lshlrev_b32_e32 v214, 16, v123
	v_and_b32_e32 v215, 0xffff0000, v123
	v_fmac_f32_e32 v82, v214, v214
	v_fmac_f32_e32 v83, v215, v215
	v_lshlrev_b32_e32 v216, 16, v124
	v_and_b32_e32 v217, 0xffff0000, v124
	v_fmac_f32_e32 v82, v216, v216
	v_fmac_f32_e32 v83, v217, v217
	v_lshlrev_b32_e32 v218, 16, v125
	v_and_b32_e32 v219, 0xffff0000, v125
	v_fmac_f32_e32 v82, v218, v218
	v_fmac_f32_e32 v83, v219, v219
	v_lshlrev_b32_e32 v212, 16, v126
	v_and_b32_e32 v213, 0xffff0000, v126
	v_fmac_f32_e32 v82, v212, v212
	v_fmac_f32_e32 v83, v213, v213
	v_lshlrev_b32_e32 v214, 16, v127
	v_and_b32_e32 v215, 0xffff0000, v127
	v_fmac_f32_e32 v82, v214, v214
	v_fmac_f32_e32 v83, v215, v215
	v_lshlrev_b32_e32 v216, 16, v128
	v_and_b32_e32 v217, 0xffff0000, v128
	v_fmac_f32_e32 v82, v216, v216
	v_fmac_f32_e32 v83, v217, v217
	v_lshlrev_b32_e32 v218, 16, v129
	v_and_b32_e32 v219, 0xffff0000, v129
	v_fmac_f32_e32 v82, v218, v218
	v_fmac_f32_e32 v83, v219, v219
	s_waitcnt vmcnt(12)
	v_lshlrev_b32_e32 v212, 16, v130
	v_and_b32_e32 v213, 0xffff0000, v130
	v_mul_f32_e32 v84, v212, v212
	v_mul_f32_e32 v85, v213, v213
	v_lshlrev_b32_e32 v214, 16, v131
	v_and_b32_e32 v215, 0xffff0000, v131
	v_fmac_f32_e32 v84, v214, v214
	v_fmac_f32_e32 v85, v215, v215
	v_lshlrev_b32_e32 v216, 16, v132
	v_and_b32_e32 v217, 0xffff0000, v132
	v_fmac_f32_e32 v84, v216, v216
	v_fmac_f32_e32 v85, v217, v217
	v_lshlrev_b32_e32 v218, 16, v133
	v_and_b32_e32 v219, 0xffff0000, v133
	v_fmac_f32_e32 v84, v218, v218
	v_fmac_f32_e32 v85, v219, v219
	v_lshlrev_b32_e32 v212, 16, v134
	v_and_b32_e32 v213, 0xffff0000, v134
	v_fmac_f32_e32 v84, v212, v212
	v_fmac_f32_e32 v85, v213, v213
	v_lshlrev_b32_e32 v214, 16, v135
	v_and_b32_e32 v215, 0xffff0000, v135
	v_fmac_f32_e32 v84, v214, v214
	v_fmac_f32_e32 v85, v215, v215
	v_lshlrev_b32_e32 v216, 16, v136
	v_and_b32_e32 v217, 0xffff0000, v136
	v_fmac_f32_e32 v84, v216, v216
	v_fmac_f32_e32 v85, v217, v217
	v_lshlrev_b32_e32 v218, 16, v137
	v_and_b32_e32 v219, 0xffff0000, v137
	v_fmac_f32_e32 v84, v218, v218
	v_fmac_f32_e32 v85, v219, v219
	s_waitcnt vmcnt(10)
	v_lshlrev_b32_e32 v212, 16, v138
	v_and_b32_e32 v213, 0xffff0000, v138
	v_mul_f32_e32 v86, v212, v212
	v_mul_f32_e32 v87, v213, v213
	v_lshlrev_b32_e32 v214, 16, v139
	v_and_b32_e32 v215, 0xffff0000, v139
	v_fmac_f32_e32 v86, v214, v214
	v_fmac_f32_e32 v87, v215, v215
	v_lshlrev_b32_e32 v216, 16, v140
	v_and_b32_e32 v217, 0xffff0000, v140
	v_fmac_f32_e32 v86, v216, v216
	v_fmac_f32_e32 v87, v217, v217
	v_lshlrev_b32_e32 v218, 16, v141
	v_and_b32_e32 v219, 0xffff0000, v141
	v_fmac_f32_e32 v86, v218, v218
	v_fmac_f32_e32 v87, v219, v219
	v_lshlrev_b32_e32 v212, 16, v142
	v_and_b32_e32 v213, 0xffff0000, v142
	v_fmac_f32_e32 v86, v212, v212
	v_fmac_f32_e32 v87, v213, v213
	v_lshlrev_b32_e32 v214, 16, v143
	v_and_b32_e32 v215, 0xffff0000, v143
	v_fmac_f32_e32 v86, v214, v214
	v_fmac_f32_e32 v87, v215, v215
	v_lshlrev_b32_e32 v216, 16, v144
	v_and_b32_e32 v217, 0xffff0000, v144
	v_fmac_f32_e32 v86, v216, v216
	v_fmac_f32_e32 v87, v217, v217
	v_lshlrev_b32_e32 v218, 16, v145
	v_and_b32_e32 v219, 0xffff0000, v145
	v_fmac_f32_e32 v86, v218, v218
	v_fmac_f32_e32 v87, v219, v219
	s_waitcnt vmcnt(8)
	v_lshlrev_b32_e32 v212, 16, v146
	v_and_b32_e32 v213, 0xffff0000, v146
	v_mul_f32_e32 v88, v212, v212
	v_mul_f32_e32 v89, v213, v213
	v_lshlrev_b32_e32 v214, 16, v147
	v_and_b32_e32 v215, 0xffff0000, v147
	v_fmac_f32_e32 v88, v214, v214
	v_fmac_f32_e32 v89, v215, v215
	v_lshlrev_b32_e32 v216, 16, v148
	v_and_b32_e32 v217, 0xffff0000, v148
	v_fmac_f32_e32 v88, v216, v216
	v_fmac_f32_e32 v89, v217, v217
	v_lshlrev_b32_e32 v218, 16, v149
	v_and_b32_e32 v219, 0xffff0000, v149
	v_fmac_f32_e32 v88, v218, v218
	v_fmac_f32_e32 v89, v219, v219
	v_lshlrev_b32_e32 v212, 16, v150
	v_and_b32_e32 v213, 0xffff0000, v150
	v_fmac_f32_e32 v88, v212, v212
	v_fmac_f32_e32 v89, v213, v213
	v_lshlrev_b32_e32 v214, 16, v151
	v_and_b32_e32 v215, 0xffff0000, v151
	v_fmac_f32_e32 v88, v214, v214
	v_fmac_f32_e32 v89, v215, v215
	v_lshlrev_b32_e32 v216, 16, v152
	v_and_b32_e32 v217, 0xffff0000, v152
	v_fmac_f32_e32 v88, v216, v216
	v_fmac_f32_e32 v89, v217, v217
	v_lshlrev_b32_e32 v218, 16, v153
	v_and_b32_e32 v219, 0xffff0000, v153
	v_fmac_f32_e32 v88, v218, v218
	v_fmac_f32_e32 v89, v219, v219
	s_waitcnt vmcnt(6)
	v_lshlrev_b32_e32 v212, 16, v154
	v_and_b32_e32 v213, 0xffff0000, v154
	v_mul_f32_e32 v90, v212, v212
	v_mul_f32_e32 v91, v213, v213
	v_lshlrev_b32_e32 v214, 16, v155
	v_and_b32_e32 v215, 0xffff0000, v155
	v_fmac_f32_e32 v90, v214, v214
	v_fmac_f32_e32 v91, v215, v215
	v_lshlrev_b32_e32 v216, 16, v156
	v_and_b32_e32 v217, 0xffff0000, v156
	v_fmac_f32_e32 v90, v216, v216
	v_fmac_f32_e32 v91, v217, v217
	v_lshlrev_b32_e32 v218, 16, v157
	v_and_b32_e32 v219, 0xffff0000, v157
	v_fmac_f32_e32 v90, v218, v218
	v_fmac_f32_e32 v91, v219, v219
	v_lshlrev_b32_e32 v212, 16, v158
	v_and_b32_e32 v213, 0xffff0000, v158
	v_fmac_f32_e32 v90, v212, v212
	v_fmac_f32_e32 v91, v213, v213
	v_lshlrev_b32_e32 v214, 16, v159
	v_and_b32_e32 v215, 0xffff0000, v159
	v_fmac_f32_e32 v90, v214, v214
	v_fmac_f32_e32 v91, v215, v215
	v_lshlrev_b32_e32 v216, 16, v160
	v_and_b32_e32 v217, 0xffff0000, v160
	v_fmac_f32_e32 v90, v216, v216
	v_fmac_f32_e32 v91, v217, v217
	v_lshlrev_b32_e32 v218, 16, v161
	v_and_b32_e32 v219, 0xffff0000, v161
	v_fmac_f32_e32 v90, v218, v218
	v_fmac_f32_e32 v91, v219, v219
	s_waitcnt vmcnt(4)
	v_lshlrev_b32_e32 v212, 16, v162
	v_and_b32_e32 v213, 0xffff0000, v162
	v_mul_f32_e32 v92, v212, v212
	v_mul_f32_e32 v93, v213, v213
	v_lshlrev_b32_e32 v214, 16, v163
	v_and_b32_e32 v215, 0xffff0000, v163
	v_fmac_f32_e32 v92, v214, v214
	v_fmac_f32_e32 v93, v215, v215
	v_lshlrev_b32_e32 v216, 16, v164
	v_and_b32_e32 v217, 0xffff0000, v164
	v_fmac_f32_e32 v92, v216, v216
	v_fmac_f32_e32 v93, v217, v217
	v_lshlrev_b32_e32 v218, 16, v165
	v_and_b32_e32 v219, 0xffff0000, v165
	v_fmac_f32_e32 v92, v218, v218
	v_fmac_f32_e32 v93, v219, v219
	v_lshlrev_b32_e32 v212, 16, v166
	v_and_b32_e32 v213, 0xffff0000, v166
	v_fmac_f32_e32 v92, v212, v212
	v_fmac_f32_e32 v93, v213, v213
	v_lshlrev_b32_e32 v214, 16, v167
	v_and_b32_e32 v215, 0xffff0000, v167
	v_fmac_f32_e32 v92, v214, v214
	v_fmac_f32_e32 v93, v215, v215
	v_lshlrev_b32_e32 v216, 16, v168
	v_and_b32_e32 v217, 0xffff0000, v168
	v_fmac_f32_e32 v92, v216, v216
	v_fmac_f32_e32 v93, v217, v217
	v_lshlrev_b32_e32 v218, 16, v169
	v_and_b32_e32 v219, 0xffff0000, v169
	v_fmac_f32_e32 v92, v218, v218
	v_fmac_f32_e32 v93, v219, v219
	s_waitcnt vmcnt(2)
	v_lshlrev_b32_e32 v212, 16, v170
	v_and_b32_e32 v213, 0xffff0000, v170
	v_mul_f32_e32 v94, v212, v212
	v_mul_f32_e32 v95, v213, v213
	v_lshlrev_b32_e32 v214, 16, v171
	v_and_b32_e32 v215, 0xffff0000, v171
	v_fmac_f32_e32 v94, v214, v214
	v_fmac_f32_e32 v95, v215, v215
	v_lshlrev_b32_e32 v216, 16, v172
	v_and_b32_e32 v217, 0xffff0000, v172
	v_fmac_f32_e32 v94, v216, v216
	v_fmac_f32_e32 v95, v217, v217
	v_lshlrev_b32_e32 v218, 16, v173
	v_and_b32_e32 v219, 0xffff0000, v173
	v_fmac_f32_e32 v94, v218, v218
	v_fmac_f32_e32 v95, v219, v219
	v_lshlrev_b32_e32 v212, 16, v174
	v_and_b32_e32 v213, 0xffff0000, v174
	v_fmac_f32_e32 v94, v212, v212
	v_fmac_f32_e32 v95, v213, v213
	v_lshlrev_b32_e32 v214, 16, v175
	v_and_b32_e32 v215, 0xffff0000, v175
	v_fmac_f32_e32 v94, v214, v214
	v_fmac_f32_e32 v95, v215, v215
	v_lshlrev_b32_e32 v216, 16, v176
	v_and_b32_e32 v217, 0xffff0000, v176
	v_fmac_f32_e32 v94, v216, v216
	v_fmac_f32_e32 v95, v217, v217
	v_lshlrev_b32_e32 v218, 16, v177
	v_and_b32_e32 v219, 0xffff0000, v177
	v_fmac_f32_e32 v94, v218, v218
	v_fmac_f32_e32 v95, v219, v219
	s_waitcnt vmcnt(0)
	v_lshlrev_b32_e32 v212, 16, v178
	v_and_b32_e32 v213, 0xffff0000, v178
	v_mul_f32_e32 v96, v212, v212
	v_mul_f32_e32 v97, v213, v213
	v_lshlrev_b32_e32 v214, 16, v179
	v_and_b32_e32 v215, 0xffff0000, v179
	v_fmac_f32_e32 v96, v214, v214
	v_fmac_f32_e32 v97, v215, v215
	v_lshlrev_b32_e32 v216, 16, v180
	v_and_b32_e32 v217, 0xffff0000, v180
	v_fmac_f32_e32 v96, v216, v216
	v_fmac_f32_e32 v97, v217, v217
	v_lshlrev_b32_e32 v218, 16, v181
	v_and_b32_e32 v219, 0xffff0000, v181
	v_fmac_f32_e32 v96, v218, v218
	v_fmac_f32_e32 v97, v219, v219
	v_lshlrev_b32_e32 v212, 16, v182
	v_and_b32_e32 v213, 0xffff0000, v182
	v_fmac_f32_e32 v96, v212, v212
	v_fmac_f32_e32 v97, v213, v213
	v_lshlrev_b32_e32 v214, 16, v183
	v_and_b32_e32 v215, 0xffff0000, v183
	v_fmac_f32_e32 v96, v214, v214
	v_fmac_f32_e32 v97, v215, v215
	v_lshlrev_b32_e32 v216, 16, v184
	v_and_b32_e32 v217, 0xffff0000, v184
	v_fmac_f32_e32 v96, v216, v216
	v_fmac_f32_e32 v97, v217, v217
	v_lshlrev_b32_e32 v218, 16, v185
	v_and_b32_e32 v219, 0xffff0000, v185
	v_fmac_f32_e32 v96, v218, v218
	v_fmac_f32_e32 v97, v219, v219
	v_add_f32_e32 v82, v82, v83
	v_add_f32_e32 v84, v84, v85
	v_add_f32_e32 v86, v86, v87
	v_add_f32_e32 v88, v88, v89
	v_add_f32_e32 v90, v90, v91
	v_add_f32_e32 v92, v92, v93
	v_add_f32_e32 v94, v94, v95
	v_add_f32_e32 v96, v96, v97
	v_add_f32_dpp v82, v82, v82 quad_perm:[1,0,3,2] row_mask:0xf bank_mask:0xf
	v_add_f32_dpp v84, v84, v84 quad_perm:[1,0,3,2] row_mask:0xf bank_mask:0xf
	v_add_f32_dpp v86, v86, v86 quad_perm:[1,0,3,2] row_mask:0xf bank_mask:0xf
	v_add_f32_dpp v88, v88, v88 quad_perm:[1,0,3,2] row_mask:0xf bank_mask:0xf
	v_add_f32_dpp v90, v90, v90 quad_perm:[1,0,3,2] row_mask:0xf bank_mask:0xf
	v_add_f32_dpp v92, v92, v92 quad_perm:[1,0,3,2] row_mask:0xf bank_mask:0xf
	v_add_f32_dpp v94, v94, v94 quad_perm:[1,0,3,2] row_mask:0xf bank_mask:0xf
	v_add_f32_dpp v96, v96, v96 quad_perm:[1,0,3,2] row_mask:0xf bank_mask:0xf
	v_add_f32_dpp v82, v82, v82 quad_perm:[2,3,0,1] row_mask:0xf bank_mask:0xf
	v_add_f32_dpp v84, v84, v84 quad_perm:[2,3,0,1] row_mask:0xf bank_mask:0xf
	v_add_f32_dpp v86, v86, v86 quad_perm:[2,3,0,1] row_mask:0xf bank_mask:0xf
	v_add_f32_dpp v88, v88, v88 quad_perm:[2,3,0,1] row_mask:0xf bank_mask:0xf
	v_add_f32_dpp v90, v90, v90 quad_perm:[2,3,0,1] row_mask:0xf bank_mask:0xf
	v_add_f32_dpp v92, v92, v92 quad_perm:[2,3,0,1] row_mask:0xf bank_mask:0xf
	v_add_f32_dpp v94, v94, v94 quad_perm:[2,3,0,1] row_mask:0xf bank_mask:0xf
	v_add_f32_dpp v96, v96, v96 quad_perm:[2,3,0,1] row_mask:0xf bank_mask:0xf
	v_add_f32_dpp v82, v82, v82 row_half_mirror row_mask:0xf bank_mask:0xf
	v_add_f32_dpp v84, v84, v84 row_half_mirror row_mask:0xf bank_mask:0xf
	v_add_f32_dpp v86, v86, v86 row_half_mirror row_mask:0xf bank_mask:0xf
	v_add_f32_dpp v88, v88, v88 row_half_mirror row_mask:0xf bank_mask:0xf
	v_add_f32_dpp v90, v90, v90 row_half_mirror row_mask:0xf bank_mask:0xf
	v_add_f32_dpp v92, v92, v92 row_half_mirror row_mask:0xf bank_mask:0xf
	v_add_f32_dpp v94, v94, v94 row_half_mirror row_mask:0xf bank_mask:0xf
	v_add_f32_dpp v96, v96, v96 row_half_mirror row_mask:0xf bank_mask:0xf
	v_add_f32_dpp v82, v82, v82 row_mirror row_mask:0xf bank_mask:0xf
	v_add_f32_dpp v84, v84, v84 row_mirror row_mask:0xf bank_mask:0xf
	v_add_f32_dpp v86, v86, v86 row_mirror row_mask:0xf bank_mask:0xf
	v_add_f32_dpp v88, v88, v88 row_mirror row_mask:0xf bank_mask:0xf
	v_add_f32_dpp v90, v90, v90 row_mirror row_mask:0xf bank_mask:0xf
	v_add_f32_dpp v92, v92, v92 row_mirror row_mask:0xf bank_mask:0xf
	v_add_f32_dpp v94, v94, v94 row_mirror row_mask:0xf bank_mask:0xf
	v_add_f32_dpp v96, v96, v96 row_mirror row_mask:0xf bank_mask:0xf
	v_add_f32_dpp v82, v82, v82 row_bcast:15 row_mask:0xa bank_mask:0xf
	v_add_f32_dpp v84, v84, v84 row_bcast:15 row_mask:0xa bank_mask:0xf
	v_add_f32_dpp v86, v86, v86 row_bcast:15 row_mask:0xa bank_mask:0xf
	v_add_f32_dpp v88, v88, v88 row_bcast:15 row_mask:0xa bank_mask:0xf
	v_add_f32_dpp v90, v90, v90 row_bcast:15 row_mask:0xa bank_mask:0xf
	v_add_f32_dpp v92, v92, v92 row_bcast:15 row_mask:0xa bank_mask:0xf
	v_add_f32_dpp v94, v94, v94 row_bcast:15 row_mask:0xa bank_mask:0xf
	v_add_f32_dpp v96, v96, v96 row_bcast:15 row_mask:0xa bank_mask:0xf
	v_add_f32_dpp v82, v82, v82 row_bcast:31 row_mask:0xc bank_mask:0xf
	v_add_f32_dpp v84, v84, v84 row_bcast:31 row_mask:0xc bank_mask:0xf
	v_add_f32_dpp v86, v86, v86 row_bcast:31 row_mask:0xc bank_mask:0xf
	v_add_f32_dpp v88, v88, v88 row_bcast:31 row_mask:0xc bank_mask:0xf
	v_add_f32_dpp v90, v90, v90 row_bcast:31 row_mask:0xc bank_mask:0xf
	v_add_f32_dpp v92, v92, v92 row_bcast:31 row_mask:0xc bank_mask:0xf
	v_add_f32_dpp v94, v94, v94 row_bcast:31 row_mask:0xc bank_mask:0xf
	v_add_f32_dpp v96, v96, v96 row_bcast:31 row_mask:0xc bank_mask:0xf
	v_readlane_b32 vcc_lo, v82, 63
	v_readlane_b32 vcc_hi, v84, 63
	s_nop 1
	v_fma_f32 v196, vcc_lo, v220, v221
	v_fma_f32 v198, vcc_hi, v220, v221
	s_nop 1
	v_readlane_b32 vcc_lo, v86, 63
	v_readlane_b32 vcc_hi, v88, 63
	s_nop 1
	v_fma_f32 v200, vcc_lo, v220, v221
	v_fma_f32 v202, vcc_hi, v220, v221
	s_nop 1
	v_readlane_b32 vcc_lo, v90, 63
	v_readlane_b32 vcc_hi, v92, 63
	s_nop 1
	v_fma_f32 v204, vcc_lo, v220, v221
	v_fma_f32 v206, vcc_hi, v220, v221
	s_nop 1
	v_readlane_b32 vcc_lo, v94, 63
	v_readlane_b32 vcc_hi, v96, 63
	s_nop 1
	v_fma_f32 v208, vcc_lo, v220, v221
	v_fma_f32 v210, vcc_hi, v220, v221
	s_nop 1
	v_rsq_f32_e32 v196, v196
	v_rsq_f32_e32 v198, v198
	v_rsq_f32_e32 v200, v200
	v_rsq_f32_e32 v202, v202
	v_rsq_f32_e32 v204, v204
	v_rsq_f32_e32 v206, v206
	v_rsq_f32_e32 v208, v208
	v_rsq_f32_e32 v210, v210
	s_nop 1
	v_lshlrev_b32_e32 v212, 16, v122
	v_and_b32_e32 v213, 0xffff0000, v122
	v_pk_mul_f32 v[212:213], v[212:213], v[196:197] op_sel_hi:[1,0]
	v_pk_fma_f32 v[212:213], v[212:213], v[66:67], v[98:99]
	v_cvt_pk_bf16_f32 v122, v212, v213
	v_lshlrev_b32_e32 v214, 16, v123
	v_and_b32_e32 v215, 0xffff0000, v123
	v_pk_mul_f32 v[214:215], v[214:215], v[196:197] op_sel_hi:[1,0]
	v_pk_fma_f32 v[214:215], v[214:215], v[68:69], v[100:101]
	v_cvt_pk_bf16_f32 v123, v214, v215
	v_lshlrev_b32_e32 v216, 16, v124
	v_and_b32_e32 v217, 0xffff0000, v124
	v_pk_mul_f32 v[216:217], v[216:217], v[196:197] op_sel_hi:[1,0]
	v_pk_fma_f32 v[216:217], v[216:217], v[70:71], v[102:103]
	v_cvt_pk_bf16_f32 v124, v216, v217
	v_lshlrev_b32_e32 v218, 16, v125
	v_and_b32_e32 v219, 0xffff0000, v125
	v_pk_mul_f32 v[218:219], v[218:219], v[196:197] op_sel_hi:[1,0]
	v_pk_fma_f32 v[218:219], v[218:219], v[72:73], v[104:105]
	v_cvt_pk_bf16_f32 v125, v218, v219
	v_lshlrev_b32_e32 v212, 16, v126
	v_and_b32_e32 v213, 0xffff0000, v126
	v_pk_mul_f32 v[212:213], v[212:213], v[196:197] op_sel_hi:[1,0]
	v_pk_fma_f32 v[212:213], v[212:213], v[74:75], v[106:107]
	v_cvt_pk_bf16_f32 v126, v212, v213
	v_lshlrev_b32_e32 v214, 16, v127
	v_and_b32_e32 v215, 0xffff0000, v127
	v_pk_mul_f32 v[214:215], v[214:215], v[196:197] op_sel_hi:[1,0]
	v_pk_fma_f32 v[214:215], v[214:215], v[76:77], v[108:109]
	v_cvt_pk_bf16_f32 v127, v214, v215
	v_lshlrev_b32_e32 v216, 16, v128
	v_and_b32_e32 v217, 0xffff0000, v128
	v_pk_mul_f32 v[216:217], v[216:217], v[196:197] op_sel_hi:[1,0]
	v_pk_fma_f32 v[216:217], v[216:217], v[78:79], v[110:111]
	v_cvt_pk_bf16_f32 v128, v216, v217
	v_lshlrev_b32_e32 v218, 16, v129
	v_and_b32_e32 v219, 0xffff0000, v129
	v_pk_mul_f32 v[218:219], v[218:219], v[196:197] op_sel_hi:[1,0]
	v_pk_fma_f32 v[218:219], v[218:219], v[80:81], v[112:113]
	v_cvt_pk_bf16_f32 v129, v218, v219
	global_store_dwordx4 v[186:187], v[122:125], off
	global_store_dwordx4 v[186:187], v[126:129], off offset:1024
	v_lshlrev_b32_e32 v212, 16, v130
	v_and_b32_e32 v213, 0xffff0000, v130
	v_pk_mul_f32 v[212:213], v[212:213], v[198:199] op_sel_hi:[1,0]
	v_pk_fma_f32 v[212:213], v[212:213], v[66:67], v[98:99]
	v_cvt_pk_bf16_f32 v130, v212, v213
	v_lshlrev_b32_e32 v214, 16, v131
	v_and_b32_e32 v215, 0xffff0000, v131
	v_pk_mul_f32 v[214:215], v[214:215], v[198:199] op_sel_hi:[1,0]
	v_pk_fma_f32 v[214:215], v[214:215], v[68:69], v[100:101]
	v_cvt_pk_bf16_f32 v131, v214, v215
	v_lshlrev_b32_e32 v216, 16, v132
	v_and_b32_e32 v217, 0xffff0000, v132
	v_pk_mul_f32 v[216:217], v[216:217], v[198:199] op_sel_hi:[1,0]
	v_pk_fma_f32 v[216:217], v[216:217], v[70:71], v[102:103]
	v_cvt_pk_bf16_f32 v132, v216, v217
	v_lshlrev_b32_e32 v218, 16, v133
	v_and_b32_e32 v219, 0xffff0000, v133
	v_pk_mul_f32 v[218:219], v[218:219], v[198:199] op_sel_hi:[1,0]
	v_pk_fma_f32 v[218:219], v[218:219], v[72:73], v[104:105]
	v_cvt_pk_bf16_f32 v133, v218, v219
	v_lshlrev_b32_e32 v212, 16, v134
	v_and_b32_e32 v213, 0xffff0000, v134
	v_pk_mul_f32 v[212:213], v[212:213], v[198:199] op_sel_hi:[1,0]
	v_pk_fma_f32 v[212:213], v[212:213], v[74:75], v[106:107]
	v_cvt_pk_bf16_f32 v134, v212, v213
	v_lshlrev_b32_e32 v214, 16, v135
	v_and_b32_e32 v215, 0xffff0000, v135
	v_pk_mul_f32 v[214:215], v[214:215], v[198:199] op_sel_hi:[1,0]
	v_pk_fma_f32 v[214:215], v[214:215], v[76:77], v[108:109]
	v_cvt_pk_bf16_f32 v135, v214, v215
	v_lshlrev_b32_e32 v216, 16, v136
	v_and_b32_e32 v217, 0xffff0000, v136
	v_pk_mul_f32 v[216:217], v[216:217], v[198:199] op_sel_hi:[1,0]
	v_pk_fma_f32 v[216:217], v[216:217], v[78:79], v[110:111]
	v_cvt_pk_bf16_f32 v136, v216, v217
	v_lshlrev_b32_e32 v218, 16, v137
	v_and_b32_e32 v219, 0xffff0000, v137
	v_pk_mul_f32 v[218:219], v[218:219], v[198:199] op_sel_hi:[1,0]
	v_pk_fma_f32 v[218:219], v[218:219], v[80:81], v[112:113]
	v_cvt_pk_bf16_f32 v137, v218, v219
	global_store_dwordx4 v[186:187], v[130:133], off offset:2048
	global_store_dwordx4 v[186:187], v[134:137], off offset:3072
	v_lshlrev_b32_e32 v212, 16, v138
	v_and_b32_e32 v213, 0xffff0000, v138
	v_pk_mul_f32 v[212:213], v[212:213], v[200:201] op_sel_hi:[1,0]
	v_pk_fma_f32 v[212:213], v[212:213], v[66:67], v[98:99]
	v_cvt_pk_bf16_f32 v138, v212, v213
	v_lshlrev_b32_e32 v214, 16, v139
	v_and_b32_e32 v215, 0xffff0000, v139
	v_pk_mul_f32 v[214:215], v[214:215], v[200:201] op_sel_hi:[1,0]
	v_pk_fma_f32 v[214:215], v[214:215], v[68:69], v[100:101]
	v_cvt_pk_bf16_f32 v139, v214, v215
	v_lshlrev_b32_e32 v216, 16, v140
	v_and_b32_e32 v217, 0xffff0000, v140
	v_pk_mul_f32 v[216:217], v[216:217], v[200:201] op_sel_hi:[1,0]
	v_pk_fma_f32 v[216:217], v[216:217], v[70:71], v[102:103]
	v_cvt_pk_bf16_f32 v140, v216, v217
	v_lshlrev_b32_e32 v218, 16, v141
	v_and_b32_e32 v219, 0xffff0000, v141
	v_pk_mul_f32 v[218:219], v[218:219], v[200:201] op_sel_hi:[1,0]
	v_pk_fma_f32 v[218:219], v[218:219], v[72:73], v[104:105]
	v_cvt_pk_bf16_f32 v141, v218, v219
	v_lshlrev_b32_e32 v212, 16, v142
	v_and_b32_e32 v213, 0xffff0000, v142
	v_pk_mul_f32 v[212:213], v[212:213], v[200:201] op_sel_hi:[1,0]
	v_pk_fma_f32 v[212:213], v[212:213], v[74:75], v[106:107]
	v_cvt_pk_bf16_f32 v142, v212, v213
	v_lshlrev_b32_e32 v214, 16, v143
	v_and_b32_e32 v215, 0xffff0000, v143
	v_pk_mul_f32 v[214:215], v[214:215], v[200:201] op_sel_hi:[1,0]
	v_pk_fma_f32 v[214:215], v[214:215], v[76:77], v[108:109]
	v_cvt_pk_bf16_f32 v143, v214, v215
	v_lshlrev_b32_e32 v216, 16, v144
	v_and_b32_e32 v217, 0xffff0000, v144
	v_pk_mul_f32 v[216:217], v[216:217], v[200:201] op_sel_hi:[1,0]
	v_pk_fma_f32 v[216:217], v[216:217], v[78:79], v[110:111]
	v_cvt_pk_bf16_f32 v144, v216, v217
	v_lshlrev_b32_e32 v218, 16, v145
	v_and_b32_e32 v219, 0xffff0000, v145
	v_pk_mul_f32 v[218:219], v[218:219], v[200:201] op_sel_hi:[1,0]
	v_pk_fma_f32 v[218:219], v[218:219], v[80:81], v[112:113]
	v_cvt_pk_bf16_f32 v145, v218, v219
	global_store_dwordx4 v[188:189], v[138:141], off
	global_store_dwordx4 v[188:189], v[142:145], off offset:1024
	v_lshlrev_b32_e32 v212, 16, v146
	v_and_b32_e32 v213, 0xffff0000, v146
	v_pk_mul_f32 v[212:213], v[212:213], v[202:203] op_sel_hi:[1,0]
	v_pk_fma_f32 v[212:213], v[212:213], v[66:67], v[98:99]
	v_cvt_pk_bf16_f32 v146, v212, v213
	v_lshlrev_b32_e32 v214, 16, v147
	v_and_b32_e32 v215, 0xffff0000, v147
	v_pk_mul_f32 v[214:215], v[214:215], v[202:203] op_sel_hi:[1,0]
	v_pk_fma_f32 v[214:215], v[214:215], v[68:69], v[100:101]
	v_cvt_pk_bf16_f32 v147, v214, v215
	v_lshlrev_b32_e32 v216, 16, v148
	v_and_b32_e32 v217, 0xffff0000, v148
	v_pk_mul_f32 v[216:217], v[216:217], v[202:203] op_sel_hi:[1,0]
	v_pk_fma_f32 v[216:217], v[216:217], v[70:71], v[102:103]
	v_cvt_pk_bf16_f32 v148, v216, v217
	v_lshlrev_b32_e32 v218, 16, v149
	v_and_b32_e32 v219, 0xffff0000, v149
	v_pk_mul_f32 v[218:219], v[218:219], v[202:203] op_sel_hi:[1,0]
	v_pk_fma_f32 v[218:219], v[218:219], v[72:73], v[104:105]
	v_cvt_pk_bf16_f32 v149, v218, v219
	v_lshlrev_b32_e32 v212, 16, v150
	v_and_b32_e32 v213, 0xffff0000, v150
	v_pk_mul_f32 v[212:213], v[212:213], v[202:203] op_sel_hi:[1,0]
	v_pk_fma_f32 v[212:213], v[212:213], v[74:75], v[106:107]
	v_cvt_pk_bf16_f32 v150, v212, v213
	v_lshlrev_b32_e32 v214, 16, v151
	v_and_b32_e32 v215, 0xffff0000, v151
	v_pk_mul_f32 v[214:215], v[214:215], v[202:203] op_sel_hi:[1,0]
	v_pk_fma_f32 v[214:215], v[214:215], v[76:77], v[108:109]
	v_cvt_pk_bf16_f32 v151, v214, v215
	v_lshlrev_b32_e32 v216, 16, v152
	v_and_b32_e32 v217, 0xffff0000, v152
	v_pk_mul_f32 v[216:217], v[216:217], v[202:203] op_sel_hi:[1,0]
	v_pk_fma_f32 v[216:217], v[216:217], v[78:79], v[110:111]
	v_cvt_pk_bf16_f32 v152, v216, v217
	v_lshlrev_b32_e32 v218, 16, v153
	v_and_b32_e32 v219, 0xffff0000, v153
	v_pk_mul_f32 v[218:219], v[218:219], v[202:203] op_sel_hi:[1,0]
	v_pk_fma_f32 v[218:219], v[218:219], v[80:81], v[112:113]
	v_cvt_pk_bf16_f32 v153, v218, v219
	global_store_dwordx4 v[188:189], v[146:149], off offset:2048
	global_store_dwordx4 v[188:189], v[150:153], off offset:3072
	v_lshlrev_b32_e32 v212, 16, v154
	v_and_b32_e32 v213, 0xffff0000, v154
	v_pk_mul_f32 v[212:213], v[212:213], v[204:205] op_sel_hi:[1,0]
	v_pk_fma_f32 v[212:213], v[212:213], v[66:67], v[98:99]
	v_cvt_pk_bf16_f32 v154, v212, v213
	v_lshlrev_b32_e32 v214, 16, v155
	v_and_b32_e32 v215, 0xffff0000, v155
	v_pk_mul_f32 v[214:215], v[214:215], v[204:205] op_sel_hi:[1,0]
	v_pk_fma_f32 v[214:215], v[214:215], v[68:69], v[100:101]
	v_cvt_pk_bf16_f32 v155, v214, v215
	v_lshlrev_b32_e32 v216, 16, v156
	v_and_b32_e32 v217, 0xffff0000, v156
	v_pk_mul_f32 v[216:217], v[216:217], v[204:205] op_sel_hi:[1,0]
	v_pk_fma_f32 v[216:217], v[216:217], v[70:71], v[102:103]
	v_cvt_pk_bf16_f32 v156, v216, v217
	v_lshlrev_b32_e32 v218, 16, v157
	v_and_b32_e32 v219, 0xffff0000, v157
	v_pk_mul_f32 v[218:219], v[218:219], v[204:205] op_sel_hi:[1,0]
	v_pk_fma_f32 v[218:219], v[218:219], v[72:73], v[104:105]
	v_cvt_pk_bf16_f32 v157, v218, v219
	v_lshlrev_b32_e32 v212, 16, v158
	v_and_b32_e32 v213, 0xffff0000, v158
	v_pk_mul_f32 v[212:213], v[212:213], v[204:205] op_sel_hi:[1,0]
	v_pk_fma_f32 v[212:213], v[212:213], v[74:75], v[106:107]
	v_cvt_pk_bf16_f32 v158, v212, v213
	v_lshlrev_b32_e32 v214, 16, v159
	v_and_b32_e32 v215, 0xffff0000, v159
	v_pk_mul_f32 v[214:215], v[214:215], v[204:205] op_sel_hi:[1,0]
	v_pk_fma_f32 v[214:215], v[214:215], v[76:77], v[108:109]
	v_cvt_pk_bf16_f32 v159, v214, v215
	v_lshlrev_b32_e32 v216, 16, v160
	v_and_b32_e32 v217, 0xffff0000, v160
	v_pk_mul_f32 v[216:217], v[216:217], v[204:205] op_sel_hi:[1,0]
	v_pk_fma_f32 v[216:217], v[216:217], v[78:79], v[110:111]
	v_cvt_pk_bf16_f32 v160, v216, v217
	v_lshlrev_b32_e32 v218, 16, v161
	v_and_b32_e32 v219, 0xffff0000, v161
	v_pk_mul_f32 v[218:219], v[218:219], v[204:205] op_sel_hi:[1,0]
	v_pk_fma_f32 v[218:219], v[218:219], v[80:81], v[112:113]
	v_cvt_pk_bf16_f32 v161, v218, v219
	global_store_dwordx4 v[190:191], v[154:157], off
	global_store_dwordx4 v[190:191], v[158:161], off offset:1024
	v_lshlrev_b32_e32 v212, 16, v162
	v_and_b32_e32 v213, 0xffff0000, v162
	v_pk_mul_f32 v[212:213], v[212:213], v[206:207] op_sel_hi:[1,0]
	v_pk_fma_f32 v[212:213], v[212:213], v[66:67], v[98:99]
	v_cvt_pk_bf16_f32 v162, v212, v213
	v_lshlrev_b32_e32 v214, 16, v163
	v_and_b32_e32 v215, 0xffff0000, v163
	v_pk_mul_f32 v[214:215], v[214:215], v[206:207] op_sel_hi:[1,0]
	v_pk_fma_f32 v[214:215], v[214:215], v[68:69], v[100:101]
	v_cvt_pk_bf16_f32 v163, v214, v215
	v_lshlrev_b32_e32 v216, 16, v164
	v_and_b32_e32 v217, 0xffff0000, v164
	v_pk_mul_f32 v[216:217], v[216:217], v[206:207] op_sel_hi:[1,0]
	v_pk_fma_f32 v[216:217], v[216:217], v[70:71], v[102:103]
	v_cvt_pk_bf16_f32 v164, v216, v217
	v_lshlrev_b32_e32 v218, 16, v165
	v_and_b32_e32 v219, 0xffff0000, v165
	v_pk_mul_f32 v[218:219], v[218:219], v[206:207] op_sel_hi:[1,0]
	v_pk_fma_f32 v[218:219], v[218:219], v[72:73], v[104:105]
	v_cvt_pk_bf16_f32 v165, v218, v219
	v_lshlrev_b32_e32 v212, 16, v166
	v_and_b32_e32 v213, 0xffff0000, v166
	v_pk_mul_f32 v[212:213], v[212:213], v[206:207] op_sel_hi:[1,0]
	v_pk_fma_f32 v[212:213], v[212:213], v[74:75], v[106:107]
	v_cvt_pk_bf16_f32 v166, v212, v213
	v_lshlrev_b32_e32 v214, 16, v167
	v_and_b32_e32 v215, 0xffff0000, v167
	v_pk_mul_f32 v[214:215], v[214:215], v[206:207] op_sel_hi:[1,0]
	v_pk_fma_f32 v[214:215], v[214:215], v[76:77], v[108:109]
	v_cvt_pk_bf16_f32 v167, v214, v215
	v_lshlrev_b32_e32 v216, 16, v168
	v_and_b32_e32 v217, 0xffff0000, v168
	v_pk_mul_f32 v[216:217], v[216:217], v[206:207] op_sel_hi:[1,0]
	v_pk_fma_f32 v[216:217], v[216:217], v[78:79], v[110:111]
	v_cvt_pk_bf16_f32 v168, v216, v217
	v_lshlrev_b32_e32 v218, 16, v169
	v_and_b32_e32 v219, 0xffff0000, v169
	v_pk_mul_f32 v[218:219], v[218:219], v[206:207] op_sel_hi:[1,0]
	v_pk_fma_f32 v[218:219], v[218:219], v[80:81], v[112:113]
	v_cvt_pk_bf16_f32 v169, v218, v219
	global_store_dwordx4 v[190:191], v[162:165], off offset:2048
	global_store_dwordx4 v[190:191], v[166:169], off offset:3072
	v_lshlrev_b32_e32 v212, 16, v170
	v_and_b32_e32 v213, 0xffff0000, v170
	v_pk_mul_f32 v[212:213], v[212:213], v[208:209] op_sel_hi:[1,0]
	v_pk_fma_f32 v[212:213], v[212:213], v[66:67], v[98:99]
	v_cvt_pk_bf16_f32 v170, v212, v213
	v_lshlrev_b32_e32 v214, 16, v171
	v_and_b32_e32 v215, 0xffff0000, v171
	v_pk_mul_f32 v[214:215], v[214:215], v[208:209] op_sel_hi:[1,0]
	v_pk_fma_f32 v[214:215], v[214:215], v[68:69], v[100:101]
	v_cvt_pk_bf16_f32 v171, v214, v215
	v_lshlrev_b32_e32 v216, 16, v172
	v_and_b32_e32 v217, 0xffff0000, v172
	v_pk_mul_f32 v[216:217], v[216:217], v[208:209] op_sel_hi:[1,0]
	v_pk_fma_f32 v[216:217], v[216:217], v[70:71], v[102:103]
	v_cvt_pk_bf16_f32 v172, v216, v217
	v_lshlrev_b32_e32 v218, 16, v173
	v_and_b32_e32 v219, 0xffff0000, v173
	v_pk_mul_f32 v[218:219], v[218:219], v[208:209] op_sel_hi:[1,0]
	v_pk_fma_f32 v[218:219], v[218:219], v[72:73], v[104:105]
	v_cvt_pk_bf16_f32 v173, v218, v219
	v_lshlrev_b32_e32 v212, 16, v174
	v_and_b32_e32 v213, 0xffff0000, v174
	v_pk_mul_f32 v[212:213], v[212:213], v[208:209] op_sel_hi:[1,0]
	v_pk_fma_f32 v[212:213], v[212:213], v[74:75], v[106:107]
	v_cvt_pk_bf16_f32 v174, v212, v213
	v_lshlrev_b32_e32 v214, 16, v175
	v_and_b32_e32 v215, 0xffff0000, v175
	v_pk_mul_f32 v[214:215], v[214:215], v[208:209] op_sel_hi:[1,0]
	v_pk_fma_f32 v[214:215], v[214:215], v[76:77], v[108:109]
	v_cvt_pk_bf16_f32 v175, v214, v215
	v_lshlrev_b32_e32 v216, 16, v176
	v_and_b32_e32 v217, 0xffff0000, v176
	v_pk_mul_f32 v[216:217], v[216:217], v[208:209] op_sel_hi:[1,0]
	v_pk_fma_f32 v[216:217], v[216:217], v[78:79], v[110:111]
	v_cvt_pk_bf16_f32 v176, v216, v217
	v_lshlrev_b32_e32 v218, 16, v177
	v_and_b32_e32 v219, 0xffff0000, v177
	v_pk_mul_f32 v[218:219], v[218:219], v[208:209] op_sel_hi:[1,0]
	v_pk_fma_f32 v[218:219], v[218:219], v[80:81], v[112:113]
	v_cvt_pk_bf16_f32 v177, v218, v219
	global_store_dwordx4 v[192:193], v[170:173], off
	global_store_dwordx4 v[192:193], v[174:177], off offset:1024
	v_lshlrev_b32_e32 v212, 16, v178
	v_and_b32_e32 v213, 0xffff0000, v178
	v_pk_mul_f32 v[212:213], v[212:213], v[210:211] op_sel_hi:[1,0]
	v_pk_fma_f32 v[212:213], v[212:213], v[66:67], v[98:99]
	v_cvt_pk_bf16_f32 v178, v212, v213
	v_lshlrev_b32_e32 v214, 16, v179
	v_and_b32_e32 v215, 0xffff0000, v179
	v_pk_mul_f32 v[214:215], v[214:215], v[210:211] op_sel_hi:[1,0]
	v_pk_fma_f32 v[214:215], v[214:215], v[68:69], v[100:101]
	v_cvt_pk_bf16_f32 v179, v214, v215
	v_lshlrev_b32_e32 v216, 16, v180
	v_and_b32_e32 v217, 0xffff0000, v180
	v_pk_mul_f32 v[216:217], v[216:217], v[210:211] op_sel_hi:[1,0]
	v_pk_fma_f32 v[216:217], v[216:217], v[70:71], v[102:103]
	v_cvt_pk_bf16_f32 v180, v216, v217
	v_lshlrev_b32_e32 v218, 16, v181
	v_and_b32_e32 v219, 0xffff0000, v181
	v_pk_mul_f32 v[218:219], v[218:219], v[210:211] op_sel_hi:[1,0]
	v_pk_fma_f32 v[218:219], v[218:219], v[72:73], v[104:105]
	v_cvt_pk_bf16_f32 v181, v218, v219
	v_lshlrev_b32_e32 v212, 16, v182
	v_and_b32_e32 v213, 0xffff0000, v182
	v_pk_mul_f32 v[212:213], v[212:213], v[210:211] op_sel_hi:[1,0]
	v_pk_fma_f32 v[212:213], v[212:213], v[74:75], v[106:107]
	v_cvt_pk_bf16_f32 v182, v212, v213
	v_lshlrev_b32_e32 v214, 16, v183
	v_and_b32_e32 v215, 0xffff0000, v183
	v_pk_mul_f32 v[214:215], v[214:215], v[210:211] op_sel_hi:[1,0]
	v_pk_fma_f32 v[214:215], v[214:215], v[76:77], v[108:109]
	v_cvt_pk_bf16_f32 v183, v214, v215
	v_lshlrev_b32_e32 v216, 16, v184
	v_and_b32_e32 v217, 0xffff0000, v184
	v_pk_mul_f32 v[216:217], v[216:217], v[210:211] op_sel_hi:[1,0]
	v_pk_fma_f32 v[216:217], v[216:217], v[78:79], v[110:111]
	v_cvt_pk_bf16_f32 v184, v216, v217
	v_lshlrev_b32_e32 v218, 16, v185
	v_and_b32_e32 v219, 0xffff0000, v185
	v_pk_mul_f32 v[218:219], v[218:219], v[210:211] op_sel_hi:[1,0]
	v_pk_fma_f32 v[218:219], v[218:219], v[80:81], v[112:113]
	v_cvt_pk_bf16_f32 v185, v218, v219
	global_store_dwordx4 v[192:193], v[178:181], off offset:2048
	global_store_dwordx4 v[192:193], v[182:185], off offset:3072
	s_mov_b32 s23, s22
.Lnf_skip:
	s_branch .LBB0_588
.LBB0_586:
	s_add_i32 s16, s23, 1
	s_cmp_ge_i32 s23, s22
	s_cselect_b64 s[14:15], -1, 0
	s_mov_b32 s23, s16

.LBB0_637:
	s_andn2_saveexec_b64 s[6:7], s[6:7]
	s_cbranch_execz .LBB0_133
	s_mov_b64 s[6:7], exec
	s_bitcmp1_b32 0xd5b56, s3
	s_cbranch_scc1 .Lskip_wbl2
	buffer_wbl2 sc1
.Lskip_wbl2:
	s_waitcnt lgkmcnt(0)
	s_waitcnt vmcnt(0)
	v_mbcnt_lo_u32_b32 v0, s6, 0
	v_mbcnt_hi_u32_b32 v0, s7, v0
	v_cmp_eq_u32_e32 vcc, 0, v0
	s_and_saveexec_b64 s[8:9], vcc
	s_cbranch_execz .LBB0_640
	s_bcnt1_i32_b64 s6, s[6:7]
	v_mov_b32_e32 v3, s6
	v_readlane_b32 s6, v249, 37
	v_readlane_b32 s7, v249, 38
	s_nop 4
	global_atomic_add v3, v1, v3, s[6:7] sc0
